# remove the per-phase s_setprio 1/0 flips inside all six GEMM K-loops (on top of the ret_chunk/P0/merge edits)
# speedup vs baseline: 1.0211x; 1.0209x over previous
.LBB0_100:
	ds_read_b128 v[146:149], v143
	ds_read_b128 v[150:153], v143 offset:1024
	ds_read_b128 v[154:157], v143 offset:2048
	ds_read_b128 v[158:161], v143 offset:3072
	s_add_u32 s20, s18, 0xfffc0080
	s_addc_u32 s21, s19, -1
	s_cmp_eq_u32 s62, 12
	s_cselect_b32 s23, s11, s21
	s_cselect_b32 s22, s50, s20
	s_cselect_b32 s21, s13, s61
	s_cselect_b32 s20, s51, s60
	v_lshl_add_u64 v[194:195], s[18:19], 0, v[132:133]
	s_add_i32 m0, s9, 0xc000
	ds_read_b128 v[162:165], v144
	ds_read_b128 v[166:169], v144 offset:1024
	ds_read_b128 v[170:173], v144 offset:2048
	ds_read_b128 v[174:177], v144 offset:3072
	ds_read_b128 v[178:181], v144 offset:4096
	ds_read_b128 v[182:185], v144 offset:5120
	ds_read_b128 v[186:189], v144 offset:6144
	ds_read_b128 v[190:193], v144 offset:7168
	global_load_lds_dwordx4 v[194:195], off
	v_lshl_add_u64 v[194:195], s[18:19], 0, v[134:135]
	s_add_i32 m0, s9, 0xe000
	s_nop 0
	global_load_lds_dwordx4 v[194:195], off
	s_waitcnt lgkmcnt(8)
	s_barrier
	s_waitcnt lgkmcnt(0)
	s_waitcnt lgkmcnt(0)
	v_mfma_f32_16x16x32_bf16 v[124:127], v[146:149], v[162:165], v[124:127]
	v_mfma_f32_16x16x32_bf16 v[120:123], v[154:157], v[162:165], v[120:123]
	v_mfma_f32_16x16x32_bf16 v[116:119], v[146:149], v[170:173], v[116:119]
	v_mfma_f32_16x16x32_bf16 v[108:111], v[154:157], v[170:173], v[108:111]
	v_mfma_f32_16x16x32_bf16 v[100:103], v[146:149], v[178:181], v[100:103]
	v_mfma_f32_16x16x32_bf16 v[92:95], v[154:157], v[178:181], v[92:95]
	v_mfma_f32_16x16x32_bf16 v[84:87], v[146:149], v[186:189], v[84:87]
	v_mfma_f32_16x16x32_bf16 v[76:79], v[154:157], v[186:189], v[76:79]
	v_mfma_f32_16x16x32_bf16 v[124:127], v[150:153], v[166:169], v[124:127]
	v_mfma_f32_16x16x32_bf16 v[120:123], v[158:161], v[166:169], v[120:123]
	v_mfma_f32_16x16x32_bf16 v[116:119], v[150:153], v[174:177], v[116:119]
	v_mfma_f32_16x16x32_bf16 v[108:111], v[158:161], v[174:177], v[108:111]
	v_mfma_f32_16x16x32_bf16 v[100:103], v[150:153], v[182:185], v[100:103]
	v_mfma_f32_16x16x32_bf16 v[92:95], v[158:161], v[182:185], v[92:95]
	v_mfma_f32_16x16x32_bf16 v[84:87], v[150:153], v[190:193], v[84:87]
	v_mfma_f32_16x16x32_bf16 v[76:79], v[158:161], v[190:193], v[76:79]
	s_barrier
	s_add_i32 s63, s47, s35
	v_lshl_add_u64 v[210:211], s[20:21], 0, v[128:129]
	s_mov_b32 m0, s63
	ds_read_b128 v[194:197], v145
	ds_read_b128 v[198:201], v145 offset:1024
	ds_read_b128 v[202:205], v145 offset:2048
	ds_read_b128 v[206:209], v145 offset:3072
	global_load_lds_dwordx4 v[210:211], off
	v_lshl_add_u64 v[212:213], s[20:21], 0, v[130:131]
	s_add_i32 m0, s63, 0x2000
	s_nop 0
	global_load_lds_dwordx4 v[212:213], off
	s_barrier
	s_waitcnt lgkmcnt(0)
	s_waitcnt lgkmcnt(0)
	v_mfma_f32_16x16x32_bf16 v[112:115], v[194:197], v[162:165], v[112:115]
	v_mfma_f32_16x16x32_bf16 v[104:107], v[202:205], v[162:165], v[104:107]
	v_mfma_f32_16x16x32_bf16 v[96:99], v[194:197], v[170:173], v[96:99]
	v_mfma_f32_16x16x32_bf16 v[88:91], v[202:205], v[170:173], v[88:91]
	v_mfma_f32_16x16x32_bf16 v[80:83], v[194:197], v[178:181], v[80:83]
	v_mfma_f32_16x16x32_bf16 v[72:75], v[202:205], v[178:181], v[72:75]
	v_mfma_f32_16x16x32_bf16 v[68:71], v[194:197], v[186:189], v[68:71]
	v_mfma_f32_16x16x32_bf16 v[64:67], v[202:205], v[186:189], v[64:67]
	v_mfma_f32_16x16x32_bf16 v[112:115], v[198:201], v[166:169], v[112:115]
	v_mfma_f32_16x16x32_bf16 v[104:107], v[206:209], v[166:169], v[104:107]
	v_mfma_f32_16x16x32_bf16 v[96:99], v[198:201], v[174:177], v[96:99]
	v_mfma_f32_16x16x32_bf16 v[88:91], v[206:209], v[174:177], v[88:91]
	v_mfma_f32_16x16x32_bf16 v[80:83], v[198:201], v[182:185], v[80:83]
	v_mfma_f32_16x16x32_bf16 v[72:75], v[206:209], v[182:185], v[72:75]
	v_mfma_f32_16x16x32_bf16 v[68:71], v[198:201], v[190:193], v[68:71]
	v_mfma_f32_16x16x32_bf16 v[64:67], v[206:209], v[190:193], v[64:67]
	s_mov_b32 m0, s9
	v_lshl_add_u64 v[214:215], s[22:23], 0, v[128:129]
	s_barrier
	ds_read_b128 v[162:165], v144 offset:16384
	ds_read_b128 v[166:169], v144 offset:17408
	ds_read_b128 v[170:173], v144 offset:18432
	ds_read_b128 v[174:177], v144 offset:19456
	ds_read_b128 v[178:181], v144 offset:20480
	ds_read_b128 v[182:185], v144 offset:21504
	ds_read_b128 v[186:189], v144 offset:22528
	ds_read_b128 v[190:193], v144 offset:23552
	global_load_lds_dwordx4 v[214:215], off
	v_lshl_add_u64 v[216:217], s[22:23], 0, v[130:131]
	s_mov_b32 m0, s36
	s_nop 0
	global_load_lds_dwordx4 v[216:217], off
	s_barrier
	s_waitcnt lgkmcnt(0)
	s_waitcnt lgkmcnt(0)
	v_mfma_f32_16x16x32_bf16 v[60:63], v[146:149], v[162:165], v[60:63]
	v_mfma_f32_16x16x32_bf16 v[56:59], v[154:157], v[162:165], v[56:59]
	v_mfma_f32_16x16x32_bf16 v[52:55], v[146:149], v[170:173], v[52:55]
	v_mfma_f32_16x16x32_bf16 v[48:51], v[154:157], v[170:173], v[48:51]
	v_mfma_f32_16x16x32_bf16 v[36:39], v[146:149], v[178:181], v[36:39]
	v_mfma_f32_16x16x32_bf16 v[32:35], v[154:157], v[178:181], v[32:35]
	v_mfma_f32_16x16x32_bf16 v[20:23], v[146:149], v[186:189], v[20:23]
	v_mfma_f32_16x16x32_bf16 v[16:19], v[154:157], v[186:189], v[16:19]
	v_mfma_f32_16x16x32_bf16 v[60:63], v[150:153], v[166:169], v[60:63]
	v_mfma_f32_16x16x32_bf16 v[56:59], v[158:161], v[166:169], v[56:59]
	v_mfma_f32_16x16x32_bf16 v[52:55], v[150:153], v[174:177], v[52:55]
	v_mfma_f32_16x16x32_bf16 v[48:51], v[158:161], v[174:177], v[48:51]
	v_mfma_f32_16x16x32_bf16 v[36:39], v[150:153], v[182:185], v[36:39]
	v_mfma_f32_16x16x32_bf16 v[32:35], v[158:161], v[182:185], v[32:35]
	v_mfma_f32_16x16x32_bf16 v[20:23], v[150:153], v[190:193], v[20:23]
	v_mfma_f32_16x16x32_bf16 v[16:19], v[158:161], v[190:193], v[16:19]
	s_barrier
	s_add_u32 s68, s20, 0x40000
	s_addc_u32 s69, s21, 0
	s_add_i32 s63, s48, s35
	v_lshl_add_u64 v[146:147], s[68:69], 0, v[128:129]
	s_mov_b32 m0, s63
	s_nop 0
	global_load_lds_dwordx4 v[146:147], off
	v_lshl_add_u64 v[146:147], s[68:69], 0, v[130:131]
	s_add_i32 m0, s63, 0x2000
	s_nop 0
	global_load_lds_dwordx4 v[146:147], off
	s_waitcnt vmcnt(6)
	s_barrier
	v_mfma_f32_16x16x32_bf16 v[44:47], v[194:197], v[162:165], v[44:47]
	v_mfma_f32_16x16x32_bf16 v[40:43], v[202:205], v[162:165], v[40:43]
	v_mfma_f32_16x16x32_bf16 v[28:31], v[194:197], v[170:173], v[28:31]
	v_mfma_f32_16x16x32_bf16 v[24:27], v[202:205], v[170:173], v[24:27]
	v_mfma_f32_16x16x32_bf16 v[12:15], v[194:197], v[178:181], v[12:15]
	v_mfma_f32_16x16x32_bf16 v[8:11], v[202:205], v[178:181], v[8:11]
	v_mfma_f32_16x16x32_bf16 v[4:7], v[194:197], v[186:189], v[4:7]
	v_mfma_f32_16x16x32_bf16 v[0:3], v[202:205], v[186:189], v[0:3]
	v_mfma_f32_16x16x32_bf16 v[44:47], v[198:201], v[166:169], v[44:47]
	v_mfma_f32_16x16x32_bf16 v[40:43], v[206:209], v[166:169], v[40:43]
	v_mfma_f32_16x16x32_bf16 v[28:31], v[198:201], v[174:177], v[28:31]
	v_mfma_f32_16x16x32_bf16 v[24:27], v[206:209], v[174:177], v[24:27]
	v_mfma_f32_16x16x32_bf16 v[12:15], v[198:201], v[182:185], v[12:15]
	v_mfma_f32_16x16x32_bf16 v[8:11], v[206:209], v[182:185], v[8:11]
	v_mfma_f32_16x16x32_bf16 v[4:7], v[198:201], v[190:193], v[4:7]
	v_mfma_f32_16x16x32_bf16 v[0:3], v[206:209], v[190:193], v[0:3]
	s_add_i32 s63, 0, 0x18000
	v_add_u32_e32 v158, s63, v141
	s_barrier
	ds_read_b128 v[146:149], v158
	ds_read_b128 v[150:153], v158 offset:1024
	ds_read_b128 v[154:157], v158 offset:2048
	ds_read_b128 v[158:161], v158 offset:3072
	s_add_u32 s22, s22, 0x40000
	s_addc_u32 s23, s23, 0
	s_mov_b32 m0, s37
	v_lshl_add_u64 v[194:195], s[22:23], 0, v[128:129]
	ds_read_b128 v[162:165], v144 offset:32768
	ds_read_b128 v[166:169], v144 offset:33792
	ds_read_b128 v[170:173], v144 offset:34816
	ds_read_b128 v[174:177], v144 offset:35840
	ds_read_b128 v[178:181], v144 offset:36864
	ds_read_b128 v[182:185], v144 offset:37888
	ds_read_b128 v[186:189], v144 offset:38912
	ds_read_b128 v[190:193], v144 offset:39936
	global_load_lds_dwordx4 v[194:195], off
	v_lshl_add_u64 v[194:195], s[22:23], 0, v[130:131]
	s_mov_b32 m0, s38
	s_nop 0
	global_load_lds_dwordx4 v[194:195], off
	s_waitcnt lgkmcnt(8)
	s_barrier
	s_waitcnt lgkmcnt(0)
	s_waitcnt lgkmcnt(0)
	v_mfma_f32_16x16x32_bf16 v[124:127], v[146:149], v[162:165], v[124:127]
	v_mfma_f32_16x16x32_bf16 v[120:123], v[154:157], v[162:165], v[120:123]
	v_mfma_f32_16x16x32_bf16 v[116:119], v[146:149], v[170:173], v[116:119]
	v_mfma_f32_16x16x32_bf16 v[108:111], v[154:157], v[170:173], v[108:111]
	v_mfma_f32_16x16x32_bf16 v[100:103], v[146:149], v[178:181], v[100:103]
	v_mfma_f32_16x16x32_bf16 v[92:95], v[154:157], v[178:181], v[92:95]
	v_mfma_f32_16x16x32_bf16 v[84:87], v[146:149], v[186:189], v[84:87]
	v_mfma_f32_16x16x32_bf16 v[76:79], v[154:157], v[186:189], v[76:79]
	v_mfma_f32_16x16x32_bf16 v[124:127], v[150:153], v[166:169], v[124:127]
	v_mfma_f32_16x16x32_bf16 v[120:123], v[158:161], v[166:169], v[120:123]
	v_mfma_f32_16x16x32_bf16 v[116:119], v[150:153], v[174:177], v[116:119]
	v_mfma_f32_16x16x32_bf16 v[108:111], v[158:161], v[174:177], v[108:111]
	v_mfma_f32_16x16x32_bf16 v[100:103], v[150:153], v[182:185], v[100:103]
	v_mfma_f32_16x16x32_bf16 v[92:95], v[158:161], v[182:185], v[92:95]
	v_mfma_f32_16x16x32_bf16 v[84:87], v[150:153], v[190:193], v[84:87]
	v_mfma_f32_16x16x32_bf16 v[76:79], v[158:161], v[190:193], v[76:79]
	s_barrier
	s_add_i32 s22, 0, 0x1c000
	s_add_i32 s23, s63, s35
	v_add_u32_e32 v206, s22, v141
	v_lshl_add_u64 v[210:211], v[210:211], 0, s[6:7]
	s_mov_b32 m0, s23
	ds_read_b128 v[194:197], v206
	ds_read_b128 v[198:201], v206 offset:1024
	ds_read_b128 v[202:205], v206 offset:2048
	ds_read_b128 v[206:209], v206 offset:3072
	global_load_lds_dwordx4 v[210:211], off
	v_lshl_add_u64 v[210:211], v[212:213], 0, s[6:7]
	s_add_i32 m0, s23, 0x2000
	s_nop 0
	global_load_lds_dwordx4 v[210:211], off
	s_barrier
	s_waitcnt lgkmcnt(0)
	s_waitcnt lgkmcnt(0)
	v_mfma_f32_16x16x32_bf16 v[112:115], v[194:197], v[162:165], v[112:115]
	v_mfma_f32_16x16x32_bf16 v[104:107], v[202:205], v[162:165], v[104:107]
	v_mfma_f32_16x16x32_bf16 v[96:99], v[194:197], v[170:173], v[96:99]
	v_mfma_f32_16x16x32_bf16 v[88:91], v[202:205], v[170:173], v[88:91]
	v_mfma_f32_16x16x32_bf16 v[80:83], v[194:197], v[178:181], v[80:83]
	v_mfma_f32_16x16x32_bf16 v[72:75], v[202:205], v[178:181], v[72:75]
	v_mfma_f32_16x16x32_bf16 v[68:71], v[194:197], v[186:189], v[68:71]
	v_mfma_f32_16x16x32_bf16 v[64:67], v[202:205], v[186:189], v[64:67]
	v_mfma_f32_16x16x32_bf16 v[112:115], v[198:201], v[166:169], v[112:115]
	v_mfma_f32_16x16x32_bf16 v[104:107], v[206:209], v[166:169], v[104:107]
	v_mfma_f32_16x16x32_bf16 v[96:99], v[198:201], v[174:177], v[96:99]
	v_mfma_f32_16x16x32_bf16 v[88:91], v[206:209], v[174:177], v[88:91]
	v_mfma_f32_16x16x32_bf16 v[80:83], v[198:201], v[182:185], v[80:83]
	v_mfma_f32_16x16x32_bf16 v[72:75], v[206:209], v[182:185], v[72:75]
	v_mfma_f32_16x16x32_bf16 v[68:71], v[198:201], v[190:193], v[68:71]
	v_mfma_f32_16x16x32_bf16 v[64:67], v[206:209], v[190:193], v[64:67]
	s_mov_b32 m0, s41
	v_lshl_add_u64 v[210:211], v[214:215], 0, s[6:7]
	s_barrier
	ds_read_b128 v[162:165], v144 offset:49152
	ds_read_b128 v[166:169], v144 offset:50176
	ds_read_b128 v[170:173], v144 offset:51200
	ds_read_b128 v[174:177], v144 offset:52224
	ds_read_b128 v[178:181], v144 offset:53248
	ds_read_b128 v[182:185], v144 offset:54272
	ds_read_b128 v[186:189], v144 offset:55296
	ds_read_b128 v[190:193], v144 offset:56320
	global_load_lds_dwordx4 v[210:211], off
	v_lshl_add_u64 v[210:211], v[216:217], 0, s[6:7]
	s_mov_b32 m0, s43
	s_nop 0
	global_load_lds_dwordx4 v[210:211], off
	s_barrier
	s_waitcnt lgkmcnt(0)
	s_waitcnt lgkmcnt(0)
	v_mfma_f32_16x16x32_bf16 v[60:63], v[146:149], v[162:165], v[60:63]
	v_mfma_f32_16x16x32_bf16 v[56:59], v[154:157], v[162:165], v[56:59]
	v_mfma_f32_16x16x32_bf16 v[52:55], v[146:149], v[170:173], v[52:55]
	v_mfma_f32_16x16x32_bf16 v[48:51], v[154:157], v[170:173], v[48:51]
	v_mfma_f32_16x16x32_bf16 v[36:39], v[146:149], v[178:181], v[36:39]
	v_mfma_f32_16x16x32_bf16 v[32:35], v[154:157], v[178:181], v[32:35]
	v_mfma_f32_16x16x32_bf16 v[20:23], v[146:149], v[186:189], v[20:23]
	v_mfma_f32_16x16x32_bf16 v[16:19], v[154:157], v[186:189], v[16:19]
	v_mfma_f32_16x16x32_bf16 v[60:63], v[150:153], v[166:169], v[60:63]
	v_mfma_f32_16x16x32_bf16 v[56:59], v[158:161], v[166:169], v[56:59]
	v_mfma_f32_16x16x32_bf16 v[52:55], v[150:153], v[174:177], v[52:55]
	v_mfma_f32_16x16x32_bf16 v[48:51], v[158:161], v[174:177], v[48:51]
	v_mfma_f32_16x16x32_bf16 v[36:39], v[150:153], v[182:185], v[36:39]
	v_mfma_f32_16x16x32_bf16 v[32:35], v[158:161], v[182:185], v[32:35]
	v_mfma_f32_16x16x32_bf16 v[20:23], v[150:153], v[190:193], v[20:23]
	v_mfma_f32_16x16x32_bf16 v[16:19], v[158:161], v[190:193], v[16:19]
	s_barrier
	s_add_u32 s20, s20, 0x40080
	s_addc_u32 s21, s21, 0
	s_add_i32 s22, s22, s35
	v_lshl_add_u64 v[146:147], s[20:21], 0, v[128:129]
	s_mov_b32 m0, s22
	s_nop 0
	global_load_lds_dwordx4 v[146:147], off
	v_lshl_add_u64 v[146:147], s[20:21], 0, v[130:131]
	s_add_i32 m0, s22, 0x2000
	s_nop 0
	global_load_lds_dwordx4 v[146:147], off
	s_waitcnt vmcnt(6)
	s_barrier
	v_mfma_f32_16x16x32_bf16 v[44:47], v[194:197], v[162:165], v[44:47]
	v_mfma_f32_16x16x32_bf16 v[40:43], v[202:205], v[162:165], v[40:43]
	v_mfma_f32_16x16x32_bf16 v[28:31], v[194:197], v[170:173], v[28:31]
	v_mfma_f32_16x16x32_bf16 v[24:27], v[202:205], v[170:173], v[24:27]
	v_mfma_f32_16x16x32_bf16 v[12:15], v[194:197], v[178:181], v[12:15]
	v_mfma_f32_16x16x32_bf16 v[8:11], v[202:205], v[178:181], v[8:11]
	v_mfma_f32_16x16x32_bf16 v[4:7], v[194:197], v[186:189], v[4:7]
	v_mfma_f32_16x16x32_bf16 v[0:3], v[202:205], v[186:189], v[0:3]
	v_mfma_f32_16x16x32_bf16 v[44:47], v[198:201], v[166:169], v[44:47]
	v_mfma_f32_16x16x32_bf16 v[40:43], v[206:209], v[166:169], v[40:43]
	v_mfma_f32_16x16x32_bf16 v[28:31], v[198:201], v[174:177], v[28:31]
	v_mfma_f32_16x16x32_bf16 v[24:27], v[206:209], v[174:177], v[24:27]
	v_mfma_f32_16x16x32_bf16 v[12:15], v[198:201], v[182:185], v[12:15]
	v_mfma_f32_16x16x32_bf16 v[8:11], v[206:209], v[182:185], v[8:11]
	v_mfma_f32_16x16x32_bf16 v[4:7], v[198:201], v[190:193], v[4:7]
	v_mfma_f32_16x16x32_bf16 v[0:3], v[206:209], v[190:193], v[0:3]
	s_add_i32 s62, s62, 2
	s_add_u32 s18, s18, 0x100
	s_addc_u32 s19, s19, 0
	s_add_u32 s60, s60, 0x100
	s_addc_u32 s61, s61, 0
	s_cmp_gt_u32 s62, 13
	s_barrier
	s_cbranch_scc0 .LBB0_100
	v_lshl_add_u32 v148, s8, 8, v140
	v_lshl_or_b32 v146, s49, 8, v142
	v_ashrrev_i32_e32 v149, 31, v148
	v_cvt_pk_bf16_f32 v112, v112, v113
	v_cvt_pk_bf16_f32 v113, v114, v115
	v_cvt_pk_bf16_f32 v114, v104, v105
	v_or_b32_e32 v104, 16, v148
	v_ashrrev_i32_e32 v147, 31, v146
	v_lshlrev_b64 v[150:151], 11, v[148:149]
	v_ashrrev_i32_e32 v105, 31, v104
	v_cvt_pk_bf16_f32 v96, v96, v97
	v_cvt_pk_bf16_f32 v97, v98, v99
	v_cvt_pk_bf16_f32 v98, v88, v89
	v_or_b32_e32 v88, 32, v148
	v_lshl_add_u64 v[150:151], s[2:3], 0, v[150:151]
	v_lshlrev_b64 v[146:147], 1, v[146:147]
	v_lshlrev_b64 v[104:105], 11, v[104:105]
	v_ashrrev_i32_e32 v89, 31, v88
	v_cvt_pk_bf16_f32 v80, v80, v81
	v_cvt_pk_bf16_f32 v81, v82, v83
	v_cvt_pk_bf16_f32 v82, v72, v73
	v_or_b32_e32 v72, 48, v148
	v_cvt_pk_bf16_f32 v68, v68, v69
	v_cvt_pk_bf16_f32 v69, v70, v71
	v_cvt_pk_bf16_f32 v70, v64, v65
	v_add_u32_e32 v64, 0x80, v148
	v_lshl_add_u64 v[150:151], v[150:151], 0, v[146:147]
	v_cvt_pk_bf16_f32 v124, v124, v125
	v_cvt_pk_bf16_f32 v125, v126, v127
	v_cvt_pk_bf16_f32 v126, v120, v121
	v_cvt_pk_bf16_f32 v127, v122, v123
	v_lshl_add_u64 v[104:105], s[2:3], 0, v[104:105]
	v_lshlrev_b64 v[88:89], 11, v[88:89]
	v_ashrrev_i32_e32 v73, 31, v72
	v_ashrrev_i32_e32 v65, 31, v64
	v_cvt_pk_bf16_f32 v44, v44, v45
	v_cvt_pk_bf16_f32 v45, v46, v47
	v_cvt_pk_bf16_f32 v46, v40, v41
	v_add_u32_e32 v40, 0x90, v148
	v_cvt_pk_bf16_f32 v115, v106, v107
	global_store_dwordx4 v[150:151], v[124:127], off
	global_store_dwordx4 v[150:151], v[112:115], off offset:64
	v_cvt_pk_bf16_f32 v106, v108, v109
	v_cvt_pk_bf16_f32 v107, v110, v111
	v_lshl_add_u64 v[112:113], v[104:105], 0, v[146:147]
	v_cvt_pk_bf16_f32 v104, v116, v117
	v_cvt_pk_bf16_f32 v105, v118, v119
	v_lshl_add_u64 v[88:89], s[2:3], 0, v[88:89]
	v_lshlrev_b64 v[72:73], 11, v[72:73]
	v_lshlrev_b64 v[64:65], 11, v[64:65]
	v_ashrrev_i32_e32 v41, 31, v40
	v_cvt_pk_bf16_f32 v28, v28, v29
	v_cvt_pk_bf16_f32 v29, v30, v31
	v_cvt_pk_bf16_f32 v30, v24, v25
	v_add_u32_e32 v24, 0xa0, v148
	v_cvt_pk_bf16_f32 v99, v90, v91
	global_store_dwordx4 v[112:113], v[104:107], off
	global_store_dwordx4 v[112:113], v[96:99], off offset:64
	v_cvt_pk_bf16_f32 v90, v92, v93
	v_cvt_pk_bf16_f32 v91, v94, v95
	v_lshl_add_u64 v[96:97], v[88:89], 0, v[146:147]
	v_cvt_pk_bf16_f32 v88, v100, v101
	v_cvt_pk_bf16_f32 v89, v102, v103
	v_lshl_add_u64 v[72:73], s[2:3], 0, v[72:73]
	v_lshl_add_u64 v[64:65], s[2:3], 0, v[64:65]
	v_lshlrev_b64 v[40:41], 11, v[40:41]
	v_ashrrev_i32_e32 v25, 31, v24
	v_cvt_pk_bf16_f32 v12, v12, v13
	v_cvt_pk_bf16_f32 v13, v14, v15
	v_cvt_pk_bf16_f32 v14, v8, v9
	v_add_u32_e32 v8, 0xb0, v148
	v_cvt_pk_bf16_f32 v83, v74, v75
	global_store_dwordx4 v[96:97], v[88:91], off
	global_store_dwordx4 v[96:97], v[80:83], off offset:64
	v_cvt_pk_bf16_f32 v74, v76, v77
	v_cvt_pk_bf16_f32 v75, v78, v79
	v_lshl_add_u64 v[80:81], v[72:73], 0, v[146:147]
	v_cvt_pk_bf16_f32 v72, v84, v85
	v_cvt_pk_bf16_f32 v73, v86, v87
	v_lshl_add_u64 v[64:65], v[64:65], 0, v[146:147]
	v_cvt_pk_bf16_f32 v60, v60, v61
	v_cvt_pk_bf16_f32 v61, v62, v63
	v_cvt_pk_bf16_f32 v62, v56, v57
	v_cvt_pk_bf16_f32 v63, v58, v59
	v_lshl_add_u64 v[40:41], s[2:3], 0, v[40:41]
	v_lshlrev_b64 v[24:25], 11, v[24:25]
	v_ashrrev_i32_e32 v9, 31, v8
	v_cvt_pk_bf16_f32 v71, v66, v67
	global_store_dwordx4 v[80:81], v[72:75], off
	global_store_dwordx4 v[80:81], v[68:71], off offset:64
	v_cvt_pk_bf16_f32 v47, v42, v43
	global_store_dwordx4 v[64:65], v[60:63], off
	global_store_dwordx4 v[64:65], v[44:47], off offset:64
	v_cvt_pk_bf16_f32 v42, v48, v49
	v_cvt_pk_bf16_f32 v43, v50, v51
	v_lshl_add_u64 v[44:45], v[40:41], 0, v[146:147]
	v_cvt_pk_bf16_f32 v40, v52, v53
	v_cvt_pk_bf16_f32 v41, v54, v55
	v_lshl_add_u64 v[24:25], s[2:3], 0, v[24:25]
	v_lshlrev_b64 v[8:9], 11, v[8:9]
	v_cvt_pk_bf16_f32 v31, v26, v27
	global_store_dwordx4 v[44:45], v[40:43], off
	global_store_dwordx4 v[44:45], v[28:31], off offset:64
	v_cvt_pk_bf16_f32 v26, v32, v33
	v_cvt_pk_bf16_f32 v27, v34, v35
	v_lshl_add_u64 v[28:29], v[24:25], 0, v[146:147]
	v_cvt_pk_bf16_f32 v24, v36, v37
	v_cvt_pk_bf16_f32 v25, v38, v39
	v_lshl_add_u64 v[8:9], s[2:3], 0, v[8:9]
	v_cvt_pk_bf16_f32 v15, v10, v11
	global_store_dwordx4 v[28:29], v[24:27], off
	global_store_dwordx4 v[28:29], v[12:15], off offset:64
	v_cvt_pk_bf16_f32 v10, v16, v17
	v_cvt_pk_bf16_f32 v11, v18, v19
	v_lshl_add_u64 v[12:13], v[8:9], 0, v[146:147]
	v_cvt_pk_bf16_f32 v8, v20, v21
	v_cvt_pk_bf16_f32 v9, v22, v23
	s_and_b64 vcc, exec, s[4:5]
	s_mov_b32 s49, s12
	s_mov_b32 s8, s10
	s_mov_b64 s[20:21], s[16:17]
	s_mov_b64 s[18:19], s[14:15]
	v_cvt_pk_bf16_f32 v4, v4, v5
	v_cvt_pk_bf16_f32 v5, v6, v7
	v_cvt_pk_bf16_f32 v6, v0, v1
	v_cvt_pk_bf16_f32 v7, v2, v3
	global_store_dwordx4 v[12:13], v[8:11], off
	global_store_dwordx4 v[12:13], v[4:7], off offset:64
	s_cbranch_vccz .LBB0_93
	s_waitcnt vmcnt(0)
	s_cmpk_gt_u32 s27, 0xff
	s_cbranch_scc1 .LBB0_104
	s_barrier

.LBB0_179:
	s_add_u32 s6, s2, 0xfffc0080
	s_addc_u32 s7, s3, -1
	s_add_i32 s33, 0, 0x10000
	v_add_u32_e32 v0, s33, v155
	ds_read_b128 v[130:133], v0
	ds_read_b128 v[134:137], v0 offset:1024
	ds_read_b128 v[138:141], v0 offset:2048
	ds_read_b128 v[142:145], v0 offset:3072
	s_cmp_eq_u32 vcc_hi, 12
	s_cselect_b32 s91, s1, s7
	s_cselect_b32 s90, s22, s6
	s_cselect_b32 s63, s23, vcc_lo
	s_cselect_b32 s62, s39, s69
	v_lshl_add_u64 v[176:177], s[2:3], 0, v[150:151]
	s_add_i32 m0, s73, 0xc000
	ds_read_b128 v[156:159], v231
	ds_read_b128 v[160:163], v231 offset:1024
	ds_read_b128 v[164:167], v231 offset:2048
	ds_read_b128 v[168:171], v231 offset:3072
	ds_read_b128 v[172:175], v231 offset:4096
	ds_read_b128 v[184:187], v231 offset:5120
	ds_read_b128 v[188:191], v231 offset:6144
	ds_read_b128 v[192:195], v231 offset:7168
	global_load_lds_dwordx4 v[176:177], off
	v_lshl_add_u64 v[176:177], s[2:3], 0, v[152:153]
	s_add_i32 m0, s73, 0xe000
	s_nop 0
	global_load_lds_dwordx4 v[176:177], off
	s_waitcnt lgkmcnt(8)
	s_barrier
	s_waitcnt lgkmcnt(0)
	s_waitcnt lgkmcnt(0)
	v_mfma_f32_16x16x32_bf16 v[126:129], v[130:133], v[156:159], v[126:129]
	v_mfma_f32_16x16x32_bf16 v[122:125], v[138:141], v[156:159], v[122:125]
	v_mfma_f32_16x16x32_bf16 v[110:113], v[130:133], v[164:167], v[110:113]
	v_mfma_f32_16x16x32_bf16 v[106:109], v[138:141], v[164:167], v[106:109]
	v_mfma_f32_16x16x32_bf16 v[94:97], v[130:133], v[172:175], v[94:97]
	v_mfma_f32_16x16x32_bf16 v[90:93], v[138:141], v[172:175], v[90:93]
	v_mfma_f32_16x16x32_bf16 v[78:81], v[130:133], v[188:191], v[78:81]
	v_mfma_f32_16x16x32_bf16 v[74:77], v[138:141], v[188:191], v[74:77]
	v_mfma_f32_16x16x32_bf16 v[126:129], v[134:137], v[160:163], v[126:129]
	v_mfma_f32_16x16x32_bf16 v[122:125], v[142:145], v[160:163], v[122:125]
	v_mfma_f32_16x16x32_bf16 v[110:113], v[134:137], v[168:171], v[110:113]
	v_mfma_f32_16x16x32_bf16 v[106:109], v[142:145], v[168:171], v[106:109]
	v_mfma_f32_16x16x32_bf16 v[94:97], v[134:137], v[184:187], v[94:97]
	v_mfma_f32_16x16x32_bf16 v[90:93], v[142:145], v[184:187], v[90:93]
	v_mfma_f32_16x16x32_bf16 v[78:81], v[134:137], v[192:195], v[78:81]
	v_mfma_f32_16x16x32_bf16 v[74:77], v[142:145], v[192:195], v[74:77]
	s_barrier
	s_add_i32 s94, 0, 0x14000
	s_add_i32 s6, s33, s11
	v_add_u32_e32 v0, s94, v155
	v_lshl_add_u64 v[176:177], s[62:63], 0, v[146:147]
	s_mov_b32 m0, s6
	ds_read_b128 v[196:199], v0
	ds_read_b128 v[200:203], v0 offset:1024
	ds_read_b128 v[204:207], v0 offset:2048
	ds_read_b128 v[208:211], v0 offset:3072
	global_load_lds_dwordx4 v[176:177], off
	v_lshl_add_u64 v[180:181], s[62:63], 0, v[148:149]
	s_add_i32 m0, s6, 0x2000
	s_nop 0
	global_load_lds_dwordx4 v[180:181], off
	s_barrier
	s_waitcnt lgkmcnt(0)
	s_waitcnt lgkmcnt(0)
	v_mfma_f32_16x16x32_bf16 v[118:121], v[196:199], v[156:159], v[118:121]
	v_mfma_f32_16x16x32_bf16 v[114:117], v[204:207], v[156:159], v[114:117]
	v_mfma_f32_16x16x32_bf16 v[102:105], v[196:199], v[164:167], v[102:105]
	v_mfma_f32_16x16x32_bf16 v[98:101], v[204:207], v[164:167], v[98:101]
	v_mfma_f32_16x16x32_bf16 v[86:89], v[196:199], v[172:175], v[86:89]
	v_mfma_f32_16x16x32_bf16 v[82:85], v[204:207], v[172:175], v[82:85]
	v_mfma_f32_16x16x32_bf16 v[70:73], v[196:199], v[188:191], v[70:73]
	v_mfma_f32_16x16x32_bf16 v[66:69], v[204:207], v[188:191], v[66:69]
	v_mfma_f32_16x16x32_bf16 v[118:121], v[200:203], v[160:163], v[118:121]
	v_mfma_f32_16x16x32_bf16 v[114:117], v[208:211], v[160:163], v[114:117]
	v_mfma_f32_16x16x32_bf16 v[102:105], v[200:203], v[168:171], v[102:105]
	v_mfma_f32_16x16x32_bf16 v[98:101], v[208:211], v[168:171], v[98:101]
	v_mfma_f32_16x16x32_bf16 v[86:89], v[200:203], v[184:187], v[86:89]
	v_mfma_f32_16x16x32_bf16 v[82:85], v[208:211], v[184:187], v[82:85]
	v_mfma_f32_16x16x32_bf16 v[70:73], v[200:203], v[192:195], v[70:73]
	v_mfma_f32_16x16x32_bf16 v[66:69], v[208:211], v[192:195], v[66:69]
	s_mov_b32 m0, s73
	v_lshl_add_u64 v[212:213], s[90:91], 0, v[146:147]
	s_barrier
	ds_read_b128 v[156:159], v231 offset:16384
	ds_read_b128 v[160:163], v231 offset:17408
	ds_read_b128 v[164:167], v231 offset:18432
	ds_read_b128 v[168:171], v231 offset:19456
	ds_read_b128 v[172:175], v231 offset:20480
	ds_read_b128 v[184:187], v231 offset:21504
	ds_read_b128 v[188:191], v231 offset:22528
	ds_read_b128 v[192:195], v231 offset:23552
	global_load_lds_dwordx4 v[212:213], off
	v_lshl_add_u64 v[214:215], s[90:91], 0, v[148:149]
	s_mov_b32 m0, s14
	s_nop 0
	global_load_lds_dwordx4 v[214:215], off
	s_barrier
	s_waitcnt lgkmcnt(0)
	s_waitcnt lgkmcnt(0)
	v_mfma_f32_16x16x32_bf16 v[62:65], v[130:133], v[156:159], v[62:65]
	v_mfma_f32_16x16x32_bf16 v[58:61], v[138:141], v[156:159], v[58:61]
	v_mfma_f32_16x16x32_bf16 v[46:49], v[130:133], v[164:167], v[46:49]
	v_mfma_f32_16x16x32_bf16 v[42:45], v[138:141], v[164:167], v[42:45]
	v_mfma_f32_16x16x32_bf16 v[30:33], v[130:133], v[172:175], v[30:33]
	v_mfma_f32_16x16x32_bf16 v[26:29], v[138:141], v[172:175], v[26:29]
	v_mfma_f32_16x16x32_bf16 v[14:17], v[130:133], v[188:191], v[14:17]
	v_mfma_f32_16x16x32_bf16 v[10:13], v[138:141], v[188:191], v[10:13]
	v_mfma_f32_16x16x32_bf16 v[62:65], v[134:137], v[160:163], v[62:65]
	v_mfma_f32_16x16x32_bf16 v[58:61], v[142:145], v[160:163], v[58:61]
	v_mfma_f32_16x16x32_bf16 v[46:49], v[134:137], v[168:171], v[46:49]
	v_mfma_f32_16x16x32_bf16 v[42:45], v[142:145], v[168:171], v[42:45]
	v_mfma_f32_16x16x32_bf16 v[30:33], v[134:137], v[184:187], v[30:33]
	v_mfma_f32_16x16x32_bf16 v[26:29], v[142:145], v[184:187], v[26:29]
	v_mfma_f32_16x16x32_bf16 v[14:17], v[134:137], v[192:195], v[14:17]
	v_mfma_f32_16x16x32_bf16 v[10:13], v[142:145], v[192:195], v[10:13]
	s_barrier
	s_add_u32 s6, s62, 0x40000
	s_addc_u32 s7, s63, 0
	s_add_i32 s33, s94, s11
	v_lshl_add_u64 v[130:131], s[6:7], 0, v[146:147]
	s_mov_b32 m0, s33
	s_nop 0
	global_load_lds_dwordx4 v[130:131], off
	v_lshl_add_u64 v[130:131], s[6:7], 0, v[148:149]
	s_add_i32 m0, s33, 0x2000
	s_nop 0
	global_load_lds_dwordx4 v[130:131], off
	s_waitcnt vmcnt(6)
	s_barrier
	v_mfma_f32_16x16x32_bf16 v[54:57], v[196:199], v[156:159], v[54:57]
	v_mfma_f32_16x16x32_bf16 v[50:53], v[204:207], v[156:159], v[50:53]
	v_mfma_f32_16x16x32_bf16 v[38:41], v[196:199], v[164:167], v[38:41]
	v_mfma_f32_16x16x32_bf16 v[34:37], v[204:207], v[164:167], v[34:37]
	v_mfma_f32_16x16x32_bf16 v[22:25], v[196:199], v[172:175], v[22:25]
	v_mfma_f32_16x16x32_bf16 v[18:21], v[204:207], v[172:175], v[18:21]
	v_mfma_f32_16x16x32_bf16 v[6:9], v[196:199], v[188:191], v[6:9]
	v_mfma_f32_16x16x32_bf16 v[2:5], v[204:207], v[188:191], v[2:5]
	v_mfma_f32_16x16x32_bf16 v[54:57], v[200:203], v[160:163], v[54:57]
	v_mfma_f32_16x16x32_bf16 v[50:53], v[208:211], v[160:163], v[50:53]
	v_mfma_f32_16x16x32_bf16 v[38:41], v[200:203], v[168:171], v[38:41]
	v_mfma_f32_16x16x32_bf16 v[34:37], v[208:211], v[168:171], v[34:37]
	v_mfma_f32_16x16x32_bf16 v[22:25], v[200:203], v[184:187], v[22:25]
	v_mfma_f32_16x16x32_bf16 v[18:21], v[208:211], v[184:187], v[18:21]
	v_mfma_f32_16x16x32_bf16 v[6:9], v[200:203], v[192:195], v[6:9]
	v_mfma_f32_16x16x32_bf16 v[2:5], v[208:211], v[192:195], v[2:5]
	s_add_i32 s33, 0, 0x18000
	v_add_u32_e32 v0, s33, v155
	s_barrier
	ds_read_b128 v[130:133], v0
	ds_read_b128 v[134:137], v0 offset:1024
	ds_read_b128 v[138:141], v0 offset:2048
	ds_read_b128 v[142:145], v0 offset:3072
	s_add_u32 s6, s90, 0x40000
	s_addc_u32 s7, s91, 0
	s_mov_b32 m0, s15
	v_lshl_add_u64 v[196:197], s[6:7], 0, v[146:147]
	ds_read_b128 v[156:159], v231 offset:32768
	ds_read_b128 v[160:163], v231 offset:33792
	ds_read_b128 v[164:167], v231 offset:34816
	ds_read_b128 v[168:171], v231 offset:35840
	ds_read_b128 v[172:175], v231 offset:36864
	ds_read_b128 v[184:187], v231 offset:37888
	ds_read_b128 v[188:191], v231 offset:38912
	ds_read_b128 v[192:195], v231 offset:39936
	global_load_lds_dwordx4 v[196:197], off
	v_lshl_add_u64 v[196:197], s[6:7], 0, v[148:149]
	s_mov_b32 m0, s16
	s_nop 0
	global_load_lds_dwordx4 v[196:197], off
	s_waitcnt lgkmcnt(8)
	s_barrier
	s_waitcnt lgkmcnt(0)
	s_waitcnt lgkmcnt(0)
	v_mfma_f32_16x16x32_bf16 v[126:129], v[130:133], v[156:159], v[126:129]
	v_mfma_f32_16x16x32_bf16 v[122:125], v[138:141], v[156:159], v[122:125]
	v_mfma_f32_16x16x32_bf16 v[110:113], v[130:133], v[164:167], v[110:113]
	v_mfma_f32_16x16x32_bf16 v[106:109], v[138:141], v[164:167], v[106:109]
	v_mfma_f32_16x16x32_bf16 v[94:97], v[130:133], v[172:175], v[94:97]
	v_mfma_f32_16x16x32_bf16 v[90:93], v[138:141], v[172:175], v[90:93]
	v_mfma_f32_16x16x32_bf16 v[78:81], v[130:133], v[188:191], v[78:81]
	v_mfma_f32_16x16x32_bf16 v[74:77], v[138:141], v[188:191], v[74:77]
	v_mfma_f32_16x16x32_bf16 v[126:129], v[134:137], v[160:163], v[126:129]
	v_mfma_f32_16x16x32_bf16 v[122:125], v[142:145], v[160:163], v[122:125]
	v_mfma_f32_16x16x32_bf16 v[110:113], v[134:137], v[168:171], v[110:113]
	v_mfma_f32_16x16x32_bf16 v[106:109], v[142:145], v[168:171], v[106:109]
	v_mfma_f32_16x16x32_bf16 v[94:97], v[134:137], v[184:187], v[94:97]
	v_mfma_f32_16x16x32_bf16 v[90:93], v[142:145], v[184:187], v[90:93]
	v_mfma_f32_16x16x32_bf16 v[78:81], v[134:137], v[192:195], v[78:81]
	v_mfma_f32_16x16x32_bf16 v[74:77], v[142:145], v[192:195], v[74:77]
	s_barrier
	s_add_i32 s90, 0, 0x1c000
	s_add_i32 s6, s33, s11
	v_add_u32_e32 v0, s90, v155
	v_lshl_add_u64 v[176:177], v[176:177], 0, s[24:25]
	s_mov_b32 m0, s6
	ds_read_b128 v[196:199], v0
	ds_read_b128 v[200:203], v0 offset:1024
	ds_read_b128 v[204:207], v0 offset:2048
	ds_read_b128 v[208:211], v0 offset:3072
	global_load_lds_dwordx4 v[176:177], off
	v_lshl_add_u64 v[176:177], v[180:181], 0, s[24:25]
	s_add_i32 m0, s6, 0x2000
	s_nop 0
	global_load_lds_dwordx4 v[176:177], off
	s_barrier
	s_waitcnt lgkmcnt(0)
	s_waitcnt lgkmcnt(0)
	v_mfma_f32_16x16x32_bf16 v[118:121], v[196:199], v[156:159], v[118:121]
	v_mfma_f32_16x16x32_bf16 v[114:117], v[204:207], v[156:159], v[114:117]
	v_mfma_f32_16x16x32_bf16 v[102:105], v[196:199], v[164:167], v[102:105]
	v_mfma_f32_16x16x32_bf16 v[98:101], v[204:207], v[164:167], v[98:101]
	v_mfma_f32_16x16x32_bf16 v[86:89], v[196:199], v[172:175], v[86:89]
	v_mfma_f32_16x16x32_bf16 v[82:85], v[204:207], v[172:175], v[82:85]
	v_mfma_f32_16x16x32_bf16 v[70:73], v[196:199], v[188:191], v[70:73]
	v_mfma_f32_16x16x32_bf16 v[66:69], v[204:207], v[188:191], v[66:69]
	v_mfma_f32_16x16x32_bf16 v[118:121], v[200:203], v[160:163], v[118:121]
	v_mfma_f32_16x16x32_bf16 v[114:117], v[208:211], v[160:163], v[114:117]
	v_mfma_f32_16x16x32_bf16 v[102:105], v[200:203], v[168:171], v[102:105]
	v_mfma_f32_16x16x32_bf16 v[98:101], v[208:211], v[168:171], v[98:101]
	v_mfma_f32_16x16x32_bf16 v[86:89], v[200:203], v[184:187], v[86:89]
	v_mfma_f32_16x16x32_bf16 v[82:85], v[208:211], v[184:187], v[82:85]
	v_mfma_f32_16x16x32_bf16 v[70:73], v[200:203], v[192:195], v[70:73]
	v_mfma_f32_16x16x32_bf16 v[66:69], v[208:211], v[192:195], v[66:69]
	s_mov_b32 m0, s18
	v_lshl_add_u64 v[176:177], v[212:213], 0, s[24:25]
	s_barrier
	ds_read_b128 v[156:159], v231 offset:49152
	ds_read_b128 v[160:163], v231 offset:50176
	ds_read_b128 v[164:167], v231 offset:51200
	ds_read_b128 v[168:171], v231 offset:52224
	ds_read_b128 v[172:175], v231 offset:53248
	ds_read_b128 v[184:187], v231 offset:54272
	ds_read_b128 v[188:191], v231 offset:55296
	ds_read_b128 v[192:195], v231 offset:56320
	global_load_lds_dwordx4 v[176:177], off
	v_lshl_add_u64 v[176:177], v[214:215], 0, s[24:25]
	s_mov_b32 m0, s19
	s_nop 0
	global_load_lds_dwordx4 v[176:177], off
	s_barrier
	s_waitcnt lgkmcnt(0)
	s_waitcnt lgkmcnt(0)
	v_mfma_f32_16x16x32_bf16 v[62:65], v[130:133], v[156:159], v[62:65]
	v_mfma_f32_16x16x32_bf16 v[58:61], v[138:141], v[156:159], v[58:61]
	v_mfma_f32_16x16x32_bf16 v[46:49], v[130:133], v[164:167], v[46:49]
	v_mfma_f32_16x16x32_bf16 v[42:45], v[138:141], v[164:167], v[42:45]
	v_mfma_f32_16x16x32_bf16 v[30:33], v[130:133], v[172:175], v[30:33]
	v_mfma_f32_16x16x32_bf16 v[26:29], v[138:141], v[172:175], v[26:29]
	v_mfma_f32_16x16x32_bf16 v[14:17], v[130:133], v[188:191], v[14:17]
	v_mfma_f32_16x16x32_bf16 v[10:13], v[138:141], v[188:191], v[10:13]
	v_mfma_f32_16x16x32_bf16 v[62:65], v[134:137], v[160:163], v[62:65]
	v_mfma_f32_16x16x32_bf16 v[58:61], v[142:145], v[160:163], v[58:61]
	v_mfma_f32_16x16x32_bf16 v[46:49], v[134:137], v[168:171], v[46:49]
	v_mfma_f32_16x16x32_bf16 v[42:45], v[142:145], v[168:171], v[42:45]
	v_mfma_f32_16x16x32_bf16 v[30:33], v[134:137], v[184:187], v[30:33]
	v_mfma_f32_16x16x32_bf16 v[26:29], v[142:145], v[184:187], v[26:29]
	v_mfma_f32_16x16x32_bf16 v[14:17], v[134:137], v[192:195], v[14:17]
	v_mfma_f32_16x16x32_bf16 v[10:13], v[142:145], v[192:195], v[10:13]
	s_barrier
	s_add_u32 s6, s62, 0x40080
	s_addc_u32 s7, s63, 0
	s_add_i32 s33, s90, s11
	v_lshl_add_u64 v[130:131], s[6:7], 0, v[146:147]
	s_mov_b32 m0, s33
	s_nop 0
	global_load_lds_dwordx4 v[130:131], off
	v_lshl_add_u64 v[130:131], s[6:7], 0, v[148:149]
	s_add_i32 m0, s33, 0x2000
	s_nop 0
	global_load_lds_dwordx4 v[130:131], off
	s_waitcnt vmcnt(6)
	s_barrier
	v_mfma_f32_16x16x32_bf16 v[54:57], v[196:199], v[156:159], v[54:57]
	v_mfma_f32_16x16x32_bf16 v[50:53], v[204:207], v[156:159], v[50:53]
	v_mfma_f32_16x16x32_bf16 v[38:41], v[196:199], v[164:167], v[38:41]
	v_mfma_f32_16x16x32_bf16 v[34:37], v[204:207], v[164:167], v[34:37]
	v_mfma_f32_16x16x32_bf16 v[22:25], v[196:199], v[172:175], v[22:25]
	v_mfma_f32_16x16x32_bf16 v[18:21], v[204:207], v[172:175], v[18:21]
	v_mfma_f32_16x16x32_bf16 v[6:9], v[196:199], v[188:191], v[6:9]
	v_mfma_f32_16x16x32_bf16 v[2:5], v[204:207], v[188:191], v[2:5]
	v_mfma_f32_16x16x32_bf16 v[54:57], v[200:203], v[160:163], v[54:57]
	v_mfma_f32_16x16x32_bf16 v[50:53], v[208:211], v[160:163], v[50:53]
	v_mfma_f32_16x16x32_bf16 v[38:41], v[200:203], v[168:171], v[38:41]
	v_mfma_f32_16x16x32_bf16 v[34:37], v[208:211], v[168:171], v[34:37]
	v_mfma_f32_16x16x32_bf16 v[22:25], v[200:203], v[184:187], v[22:25]
	v_mfma_f32_16x16x32_bf16 v[18:21], v[208:211], v[184:187], v[18:21]
	v_mfma_f32_16x16x32_bf16 v[6:9], v[200:203], v[192:195], v[6:9]
	v_mfma_f32_16x16x32_bf16 v[2:5], v[208:211], v[192:195], v[2:5]
	s_add_i32 vcc_hi, vcc_hi, 2
	s_add_u32 s2, s2, 0x100
	s_addc_u32 s3, s3, 0
	s_add_u32 s69, s69, 0x100
	s_addc_u32 vcc_lo, vcc_lo, 0
	s_cmp_gt_u32 vcc_hi, 13
	s_barrier
	s_cbranch_scc0 .LBB0_179
	s_cmp_gt_i32 s72, 17
	s_cbranch_scc0 .LBB0_182
	s_and_b32 s1, s72, 0x7ffffffe
	s_cmp_gt_u32 s72, 25
	s_cselect_b32 s2, 3, 0
	s_cmp_lg_u32 s1, 22
	s_cselect_b32 s1, s2, 4
	s_cmp_eq_u32 s72, 19
	s_cselect_b64 vcc, -1, 0
	v_mov_b32_e32 v0, 0x3e000000
	s_and_b64 s[2:3], vcc, exec
	v_cndmask_b32_e32 v154, 1.0, v0, vcc
	s_cselect_b32 s39, 2, s1
	s_movk_i32 s94, 0x2000
	s_mov_b32 s1, 0
	s_cbranch_execz .LBB0_183
	s_branch .LBB0_188

.LBB0_528:
	s_add_u32 s6, s62, 0xfffe0080
	s_addc_u32 s33, s63, -1
	s_add_i32 s72, 0, 0x10000
	v_add_u32_e32 v0, s72, v184
	ds_read_b128 v[130:133], v0
	ds_read_b128 v[134:137], v0 offset:1024
	ds_read_b128 v[138:141], v0 offset:2048
	ds_read_b128 v[142:145], v0 offset:3072
	s_cmp_eq_u32 s69, 4
	s_cselect_b32 vcc_hi, s21, s33
	s_cselect_b32 vcc_lo, s22, s6
	s_cselect_b32 s91, s23, s48
	s_cselect_b32 s90, s39, s47
	v_lshl_add_u64 v[180:181], s[62:63], 0, v[166:167]
	s_add_i32 m0, s3, 0xc000
	ds_read_b128 v[146:149], v201
	ds_read_b128 v[150:153], v201 offset:1024
	ds_read_b128 v[154:157], v201 offset:2048
	ds_read_b128 v[158:161], v201 offset:3072
	ds_read_b128 v[170:173], v201 offset:4096
	ds_read_b128 v[174:177], v201 offset:5120
	ds_read_b128 v[202:205], v201 offset:6144
	ds_read_b128 v[206:209], v201 offset:7168
	global_load_lds_dwordx4 v[180:181], off
	v_lshl_add_u64 v[180:181], s[62:63], 0, v[168:169]
	s_add_i32 m0, s3, 0xe000
	s_nop 0
	global_load_lds_dwordx4 v[180:181], off
	s_waitcnt lgkmcnt(8)
	s_barrier
	s_waitcnt lgkmcnt(0)
	s_waitcnt lgkmcnt(0)
	v_mfma_f32_16x16x32_bf16 v[126:129], v[130:133], v[146:149], v[126:129]
	v_mfma_f32_16x16x32_bf16 v[122:125], v[138:141], v[146:149], v[122:125]
	v_mfma_f32_16x16x32_bf16 v[110:113], v[130:133], v[154:157], v[110:113]
	v_mfma_f32_16x16x32_bf16 v[106:109], v[138:141], v[154:157], v[106:109]
	v_mfma_f32_16x16x32_bf16 v[94:97], v[130:133], v[170:173], v[94:97]
	v_mfma_f32_16x16x32_bf16 v[90:93], v[138:141], v[170:173], v[90:93]
	v_mfma_f32_16x16x32_bf16 v[78:81], v[130:133], v[202:205], v[78:81]
	v_mfma_f32_16x16x32_bf16 v[74:77], v[138:141], v[202:205], v[74:77]
	v_mfma_f32_16x16x32_bf16 v[126:129], v[134:137], v[150:153], v[126:129]
	v_mfma_f32_16x16x32_bf16 v[122:125], v[142:145], v[150:153], v[122:125]
	v_mfma_f32_16x16x32_bf16 v[110:113], v[134:137], v[158:161], v[110:113]
	v_mfma_f32_16x16x32_bf16 v[106:109], v[142:145], v[158:161], v[106:109]
	v_mfma_f32_16x16x32_bf16 v[94:97], v[134:137], v[174:177], v[94:97]
	v_mfma_f32_16x16x32_bf16 v[90:93], v[142:145], v[174:177], v[90:93]
	v_mfma_f32_16x16x32_bf16 v[78:81], v[134:137], v[206:209], v[78:81]
	v_mfma_f32_16x16x32_bf16 v[74:77], v[142:145], v[206:209], v[74:77]
	s_barrier
	s_add_i32 s6, 0, 0x14000
	s_add_i32 s33, s72, s14
	v_add_u32_e32 v0, s6, v184
	v_lshl_add_u64 v[180:181], s[90:91], 0, v[162:163]
	s_mov_b32 m0, s33
	ds_read_b128 v[210:213], v0
	ds_read_b128 v[214:217], v0 offset:1024
	ds_read_b128 v[218:221], v0 offset:2048
	ds_read_b128 v[222:225], v0 offset:3072
	global_load_lds_dwordx4 v[180:181], off
	v_lshl_add_u64 v[226:227], s[90:91], 0, v[164:165]
	s_add_i32 m0, s33, 0x2000
	s_nop 0
	global_load_lds_dwordx4 v[226:227], off
	s_barrier
	s_waitcnt lgkmcnt(0)
	s_waitcnt lgkmcnt(0)
	v_mfma_f32_16x16x32_bf16 v[118:121], v[210:213], v[146:149], v[118:121]
	v_mfma_f32_16x16x32_bf16 v[114:117], v[218:221], v[146:149], v[114:117]
	v_mfma_f32_16x16x32_bf16 v[102:105], v[210:213], v[154:157], v[102:105]
	v_mfma_f32_16x16x32_bf16 v[98:101], v[218:221], v[154:157], v[98:101]
	v_mfma_f32_16x16x32_bf16 v[86:89], v[210:213], v[170:173], v[86:89]
	v_mfma_f32_16x16x32_bf16 v[82:85], v[218:221], v[170:173], v[82:85]
	v_mfma_f32_16x16x32_bf16 v[70:73], v[210:213], v[202:205], v[70:73]
	v_mfma_f32_16x16x32_bf16 v[66:69], v[218:221], v[202:205], v[66:69]
	v_mfma_f32_16x16x32_bf16 v[118:121], v[214:217], v[150:153], v[118:121]
	v_mfma_f32_16x16x32_bf16 v[114:117], v[222:225], v[150:153], v[114:117]
	v_mfma_f32_16x16x32_bf16 v[102:105], v[214:217], v[158:161], v[102:105]
	v_mfma_f32_16x16x32_bf16 v[98:101], v[222:225], v[158:161], v[98:101]
	v_mfma_f32_16x16x32_bf16 v[86:89], v[214:217], v[174:177], v[86:89]
	v_mfma_f32_16x16x32_bf16 v[82:85], v[222:225], v[174:177], v[82:85]
	v_mfma_f32_16x16x32_bf16 v[70:73], v[214:217], v[206:209], v[70:73]
	v_mfma_f32_16x16x32_bf16 v[66:69], v[222:225], v[206:209], v[66:69]
	s_mov_b32 m0, s3
	v_lshl_add_u64 v[240:241], vcc, 0, v[162:163]
	s_barrier
	ds_read_b128 v[146:149], v201 offset:16384
	ds_read_b128 v[150:153], v201 offset:17408
	ds_read_b128 v[154:157], v201 offset:18432
	ds_read_b128 v[158:161], v201 offset:19456
	ds_read_b128 v[170:173], v201 offset:20480
	ds_read_b128 v[174:177], v201 offset:21504
	ds_read_b128 v[202:205], v201 offset:22528
	ds_read_b128 v[206:209], v201 offset:23552
	global_load_lds_dwordx4 v[240:241], off
	v_lshl_add_u64 v[244:245], vcc, 0, v[164:165]
	s_mov_b32 m0, s15
	s_nop 0
	global_load_lds_dwordx4 v[244:245], off
	s_barrier
	s_waitcnt lgkmcnt(0)
	s_waitcnt lgkmcnt(0)
	v_mfma_f32_16x16x32_bf16 v[62:65], v[130:133], v[146:149], v[62:65]
	v_mfma_f32_16x16x32_bf16 v[58:61], v[138:141], v[146:149], v[58:61]
	v_mfma_f32_16x16x32_bf16 v[46:49], v[130:133], v[154:157], v[46:49]
	v_mfma_f32_16x16x32_bf16 v[42:45], v[138:141], v[154:157], v[42:45]
	v_mfma_f32_16x16x32_bf16 v[30:33], v[130:133], v[170:173], v[30:33]
	v_mfma_f32_16x16x32_bf16 v[26:29], v[138:141], v[170:173], v[26:29]
	v_mfma_f32_16x16x32_bf16 v[14:17], v[130:133], v[202:205], v[14:17]
	v_mfma_f32_16x16x32_bf16 v[10:13], v[138:141], v[202:205], v[10:13]
	v_mfma_f32_16x16x32_bf16 v[62:65], v[134:137], v[150:153], v[62:65]
	v_mfma_f32_16x16x32_bf16 v[58:61], v[142:145], v[150:153], v[58:61]
	v_mfma_f32_16x16x32_bf16 v[46:49], v[134:137], v[158:161], v[46:49]
	v_mfma_f32_16x16x32_bf16 v[42:45], v[142:145], v[158:161], v[42:45]
	v_mfma_f32_16x16x32_bf16 v[30:33], v[134:137], v[174:177], v[30:33]
	v_mfma_f32_16x16x32_bf16 v[26:29], v[142:145], v[174:177], v[26:29]
	v_mfma_f32_16x16x32_bf16 v[14:17], v[134:137], v[206:209], v[14:17]
	v_mfma_f32_16x16x32_bf16 v[10:13], v[142:145], v[206:209], v[10:13]
	s_barrier
	s_add_u32 s72, s90, 0x20000
	s_addc_u32 s73, s91, 0
	s_add_i32 s6, s6, s14
	v_lshl_add_u64 v[130:131], s[72:73], 0, v[162:163]
	s_mov_b32 m0, s6
	s_nop 0
	global_load_lds_dwordx4 v[130:131], off
	v_lshl_add_u64 v[130:131], s[72:73], 0, v[164:165]
	s_add_i32 m0, s6, 0x2000
	s_nop 0
	global_load_lds_dwordx4 v[130:131], off
	s_waitcnt vmcnt(6)
	s_barrier
	v_mfma_f32_16x16x32_bf16 v[54:57], v[210:213], v[146:149], v[54:57]
	v_mfma_f32_16x16x32_bf16 v[50:53], v[218:221], v[146:149], v[50:53]
	v_mfma_f32_16x16x32_bf16 v[38:41], v[210:213], v[154:157], v[38:41]
	v_mfma_f32_16x16x32_bf16 v[34:37], v[218:221], v[154:157], v[34:37]
	v_mfma_f32_16x16x32_bf16 v[22:25], v[210:213], v[170:173], v[22:25]
	v_mfma_f32_16x16x32_bf16 v[18:21], v[218:221], v[170:173], v[18:21]
	v_mfma_f32_16x16x32_bf16 v[6:9], v[210:213], v[202:205], v[6:9]
	v_mfma_f32_16x16x32_bf16 v[2:5], v[218:221], v[202:205], v[2:5]
	v_mfma_f32_16x16x32_bf16 v[54:57], v[214:217], v[150:153], v[54:57]
	v_mfma_f32_16x16x32_bf16 v[50:53], v[222:225], v[150:153], v[50:53]
	v_mfma_f32_16x16x32_bf16 v[38:41], v[214:217], v[158:161], v[38:41]
	v_mfma_f32_16x16x32_bf16 v[34:37], v[222:225], v[158:161], v[34:37]
	v_mfma_f32_16x16x32_bf16 v[22:25], v[214:217], v[174:177], v[22:25]
	v_mfma_f32_16x16x32_bf16 v[18:21], v[222:225], v[174:177], v[18:21]
	v_mfma_f32_16x16x32_bf16 v[6:9], v[214:217], v[206:209], v[6:9]
	v_mfma_f32_16x16x32_bf16 v[2:5], v[222:225], v[206:209], v[2:5]
	s_add_i32 s6, 0, 0x18000
	v_add_u32_e32 v0, s6, v184
	s_barrier
	ds_read_b128 v[130:133], v0
	ds_read_b128 v[134:137], v0 offset:1024
	ds_read_b128 v[138:141], v0 offset:2048
	ds_read_b128 v[142:145], v0 offset:3072
	s_add_u32 s72, vcc_lo, 0x20000
	s_addc_u32 s73, vcc_hi, 0
	s_mov_b32 m0, s16
	v_lshl_add_u64 v[210:211], s[72:73], 0, v[162:163]
	ds_read_b128 v[146:149], v201 offset:32768
	ds_read_b128 v[150:153], v201 offset:33792
	ds_read_b128 v[154:157], v201 offset:34816
	ds_read_b128 v[158:161], v201 offset:35840
	ds_read_b128 v[170:173], v201 offset:36864
	ds_read_b128 v[174:177], v201 offset:37888
	ds_read_b128 v[202:205], v201 offset:38912
	ds_read_b128 v[206:209], v201 offset:39936
	global_load_lds_dwordx4 v[210:211], off
	v_lshl_add_u64 v[210:211], s[72:73], 0, v[164:165]
	s_mov_b32 m0, s17
	s_nop 0
	global_load_lds_dwordx4 v[210:211], off
	s_waitcnt lgkmcnt(8)
	s_barrier
	s_waitcnt lgkmcnt(0)
	s_waitcnt lgkmcnt(0)
	v_mfma_f32_16x16x32_bf16 v[126:129], v[130:133], v[146:149], v[126:129]
	v_mfma_f32_16x16x32_bf16 v[122:125], v[138:141], v[146:149], v[122:125]
	v_mfma_f32_16x16x32_bf16 v[110:113], v[130:133], v[154:157], v[110:113]
	v_mfma_f32_16x16x32_bf16 v[106:109], v[138:141], v[154:157], v[106:109]
	v_mfma_f32_16x16x32_bf16 v[94:97], v[130:133], v[170:173], v[94:97]
	v_mfma_f32_16x16x32_bf16 v[90:93], v[138:141], v[170:173], v[90:93]
	v_mfma_f32_16x16x32_bf16 v[78:81], v[130:133], v[202:205], v[78:81]
	v_mfma_f32_16x16x32_bf16 v[74:77], v[138:141], v[202:205], v[74:77]
	v_mfma_f32_16x16x32_bf16 v[126:129], v[134:137], v[150:153], v[126:129]
	v_mfma_f32_16x16x32_bf16 v[122:125], v[142:145], v[150:153], v[122:125]
	v_mfma_f32_16x16x32_bf16 v[110:113], v[134:137], v[158:161], v[110:113]
	v_mfma_f32_16x16x32_bf16 v[106:109], v[142:145], v[158:161], v[106:109]
	v_mfma_f32_16x16x32_bf16 v[94:97], v[134:137], v[174:177], v[94:97]
	v_mfma_f32_16x16x32_bf16 v[90:93], v[142:145], v[174:177], v[90:93]
	v_mfma_f32_16x16x32_bf16 v[78:81], v[134:137], v[206:209], v[78:81]
	v_mfma_f32_16x16x32_bf16 v[74:77], v[142:145], v[206:209], v[74:77]
	s_barrier
	s_add_i32 s33, 0, 0x1c000
	s_add_i32 s6, s6, s14
	v_add_u32_e32 v0, s33, v184
	v_lshl_add_u64 v[180:181], v[180:181], 0, s[24:25]
	s_mov_b32 m0, s6
	ds_read_b128 v[210:213], v0
	ds_read_b128 v[214:217], v0 offset:1024
	ds_read_b128 v[218:221], v0 offset:2048
	ds_read_b128 v[222:225], v0 offset:3072
	global_load_lds_dwordx4 v[180:181], off
	v_lshl_add_u64 v[180:181], v[226:227], 0, s[24:25]
	s_add_i32 m0, s6, 0x2000
	s_nop 0
	global_load_lds_dwordx4 v[180:181], off
	s_barrier
	s_waitcnt lgkmcnt(0)
	s_waitcnt lgkmcnt(0)
	v_mfma_f32_16x16x32_bf16 v[118:121], v[210:213], v[146:149], v[118:121]
	v_mfma_f32_16x16x32_bf16 v[114:117], v[218:221], v[146:149], v[114:117]
	v_mfma_f32_16x16x32_bf16 v[102:105], v[210:213], v[154:157], v[102:105]
	v_mfma_f32_16x16x32_bf16 v[98:101], v[218:221], v[154:157], v[98:101]
	v_mfma_f32_16x16x32_bf16 v[86:89], v[210:213], v[170:173], v[86:89]
	v_mfma_f32_16x16x32_bf16 v[82:85], v[218:221], v[170:173], v[82:85]
	v_mfma_f32_16x16x32_bf16 v[70:73], v[210:213], v[202:205], v[70:73]
	v_mfma_f32_16x16x32_bf16 v[66:69], v[218:221], v[202:205], v[66:69]
	v_mfma_f32_16x16x32_bf16 v[118:121], v[214:217], v[150:153], v[118:121]
	v_mfma_f32_16x16x32_bf16 v[114:117], v[222:225], v[150:153], v[114:117]
	v_mfma_f32_16x16x32_bf16 v[102:105], v[214:217], v[158:161], v[102:105]
	v_mfma_f32_16x16x32_bf16 v[98:101], v[222:225], v[158:161], v[98:101]
	v_mfma_f32_16x16x32_bf16 v[86:89], v[214:217], v[174:177], v[86:89]
	v_mfma_f32_16x16x32_bf16 v[82:85], v[222:225], v[174:177], v[82:85]
	v_mfma_f32_16x16x32_bf16 v[70:73], v[214:217], v[206:209], v[70:73]
	v_mfma_f32_16x16x32_bf16 v[66:69], v[222:225], v[206:209], v[66:69]
	s_mov_b32 m0, s7
	v_lshl_add_u64 v[180:181], v[240:241], 0, s[24:25]
	s_barrier
	ds_read_b128 v[146:149], v201 offset:49152
	ds_read_b128 v[150:153], v201 offset:50176
	ds_read_b128 v[154:157], v201 offset:51200
	ds_read_b128 v[158:161], v201 offset:52224
	ds_read_b128 v[170:173], v201 offset:53248
	ds_read_b128 v[174:177], v201 offset:54272
	ds_read_b128 v[202:205], v201 offset:55296
	ds_read_b128 v[206:209], v201 offset:56320
	global_load_lds_dwordx4 v[180:181], off
	v_lshl_add_u64 v[180:181], v[244:245], 0, s[24:25]
	s_mov_b32 m0, s18
	s_nop 0
	global_load_lds_dwordx4 v[180:181], off
	s_barrier
	s_waitcnt lgkmcnt(0)
	s_waitcnt lgkmcnt(0)
	v_mfma_f32_16x16x32_bf16 v[62:65], v[130:133], v[146:149], v[62:65]
	v_mfma_f32_16x16x32_bf16 v[58:61], v[138:141], v[146:149], v[58:61]
	v_mfma_f32_16x16x32_bf16 v[46:49], v[130:133], v[154:157], v[46:49]
	v_mfma_f32_16x16x32_bf16 v[42:45], v[138:141], v[154:157], v[42:45]
	v_mfma_f32_16x16x32_bf16 v[30:33], v[130:133], v[170:173], v[30:33]
	v_mfma_f32_16x16x32_bf16 v[26:29], v[138:141], v[170:173], v[26:29]
	v_mfma_f32_16x16x32_bf16 v[14:17], v[130:133], v[202:205], v[14:17]
	v_mfma_f32_16x16x32_bf16 v[10:13], v[138:141], v[202:205], v[10:13]
	v_mfma_f32_16x16x32_bf16 v[62:65], v[134:137], v[150:153], v[62:65]
	v_mfma_f32_16x16x32_bf16 v[58:61], v[142:145], v[150:153], v[58:61]
	v_mfma_f32_16x16x32_bf16 v[46:49], v[134:137], v[158:161], v[46:49]
	v_mfma_f32_16x16x32_bf16 v[42:45], v[142:145], v[158:161], v[42:45]
	v_mfma_f32_16x16x32_bf16 v[30:33], v[134:137], v[174:177], v[30:33]
	v_mfma_f32_16x16x32_bf16 v[26:29], v[142:145], v[174:177], v[26:29]
	v_mfma_f32_16x16x32_bf16 v[14:17], v[134:137], v[206:209], v[14:17]
	v_mfma_f32_16x16x32_bf16 v[10:13], v[142:145], v[206:209], v[10:13]
	s_barrier
	s_add_u32 s72, s90, 0x20080
	s_addc_u32 s73, s91, 0
	s_add_i32 s6, s33, s14
	v_lshl_add_u64 v[130:131], s[72:73], 0, v[162:163]
	s_mov_b32 m0, s6
	s_nop 0
	global_load_lds_dwordx4 v[130:131], off
	v_lshl_add_u64 v[130:131], s[72:73], 0, v[164:165]
	s_add_i32 m0, s6, 0x2000
	s_nop 0
	global_load_lds_dwordx4 v[130:131], off
	s_waitcnt vmcnt(6)
	s_barrier
	v_mfma_f32_16x16x32_bf16 v[54:57], v[210:213], v[146:149], v[54:57]
	v_mfma_f32_16x16x32_bf16 v[50:53], v[218:221], v[146:149], v[50:53]
	v_mfma_f32_16x16x32_bf16 v[38:41], v[210:213], v[154:157], v[38:41]
	v_mfma_f32_16x16x32_bf16 v[34:37], v[218:221], v[154:157], v[34:37]
	v_mfma_f32_16x16x32_bf16 v[22:25], v[210:213], v[170:173], v[22:25]
	v_mfma_f32_16x16x32_bf16 v[18:21], v[218:221], v[170:173], v[18:21]
	v_mfma_f32_16x16x32_bf16 v[6:9], v[210:213], v[202:205], v[6:9]
	v_mfma_f32_16x16x32_bf16 v[2:5], v[218:221], v[202:205], v[2:5]
	v_mfma_f32_16x16x32_bf16 v[54:57], v[214:217], v[150:153], v[54:57]
	v_mfma_f32_16x16x32_bf16 v[50:53], v[222:225], v[150:153], v[50:53]
	v_mfma_f32_16x16x32_bf16 v[38:41], v[214:217], v[158:161], v[38:41]
	v_mfma_f32_16x16x32_bf16 v[34:37], v[222:225], v[158:161], v[34:37]
	v_mfma_f32_16x16x32_bf16 v[22:25], v[214:217], v[174:177], v[22:25]
	v_mfma_f32_16x16x32_bf16 v[18:21], v[222:225], v[174:177], v[18:21]
	v_mfma_f32_16x16x32_bf16 v[6:9], v[214:217], v[206:209], v[6:9]
	v_mfma_f32_16x16x32_bf16 v[2:5], v[222:225], v[206:209], v[2:5]
	s_add_i32 s69, s69, 2
	s_add_u32 s62, s62, 0x100
	s_addc_u32 s63, s63, 0
	s_add_u32 s47, s47, 0x100
	s_addc_u32 s48, s48, 0
	s_cmp_gt_u32 s69, 5
	s_barrier
	s_cbranch_scc0 .LBB0_528
	s_lshl_b32 s21, s38, 8
	s_ashr_i32 s6, s38, 2
	s_and_b32 s21, s21, 0x300
	s_cmp_lt_u32 s38, 4
	s_cselect_b64 s[62:63], -1, 0
	s_cmp_gt_u32 s38, 3
	s_cselect_b64 s[90:91], -1, 0
	s_lshl_b32 s22, s6, 15
	s_lshl_b32 s2, s2, 8
	s_lshl_b32 s6, s6, 10
	v_or_b32_e32 v132, s21, v200
	s_sub_i32 s2, s2, s22
	s_addk_i32 s6, 0x1a00
	v_add_u32_e32 v0, s6, v132
	v_add_u32_e32 v170, s2, v179
	v_ashrrev_i32_e32 v203, 8, v0
	v_lshrrev_b32_e32 v0, 8, v170
	v_mad_i32_i24 v130, v0, 38, v203
	v_bitop3_b32 v202, s21, v243, v200 bitop3:0xc8
	v_ashrrev_i32_e32 v131, 31, v130
	v_or_b32_e32 v0, v202, v185
	v_lshlrev_b64 v[130:131], 17, v[130:131]
	v_lshl_add_u64 v[130:131], s[40:41], 0, v[130:131]
	v_lshlrev_b32_e32 v0, 1, v0
	v_lshl_add_u64 v[130:131], v[130:131], 0, v[0:1]
	global_load_dwordx4 v[154:157], v[130:131], off
	global_load_dwordx4 v[138:141], v[130:131], off offset:64
	v_lshlrev_b32_e32 v172, 1, v132
	v_mov_b32_e32 v173, v1
	v_lshl_add_u64 v[176:177], s[0:1], 0, v[172:173]
	v_mov_b32_e32 v130, 0
	s_and_b64 vcc, exec, s[62:63]
	v_ashrrev_i32_e32 v171, 31, v170
	v_mov_b32_e32 v146, 0
	v_mov_b32_e32 v147, 0
	v_mov_b32_e32 v148, 0
	v_mov_b32_e32 v149, 0
	v_mov_b32_e32 v158, 0
	v_mov_b32_e32 v159, 0
	v_mov_b32_e32 v160, 0
	v_mov_b32_e32 v161, 0
	s_cbranch_vccnz .LBB0_531
	v_lshlrev_b64 v[132:133], 11, v[170:171]
	v_lshl_add_u64 v[132:133], v[176:177], 0, v[132:133]
	global_load_dwordx4 v[158:161], v[132:133], off
	global_load_dwordx4 v[146:149], v[132:133], off offset:64

.LBB0_618:
	ds_read_b128 v[48:51], v185
	ds_read_b128 v[52:55], v185 offset:1024
	ds_read_b128 v[56:59], v185 offset:2048
	ds_read_b128 v[60:63], v185 offset:3072
	s_add_u32 s47, s48, 0xfffc0080
	s_addc_u32 s50, s49, -1
	s_cmp_eq_u32 s35, 12
	s_cselect_b32 s55, s3, s50
	s_cselect_b32 s54, s21, s47
	s_cselect_b32 s53, s22, s33
	s_cselect_b32 s52, s23, s31
	v_lshl_add_u64 v[180:181], s[48:49], 0, v[164:165]
	s_add_i32 m0, s11, 0xc000
	ds_read_b128 v[144:147], v186
	ds_read_b128 v[148:151], v186 offset:1024
	ds_read_b128 v[152:155], v186 offset:2048
	ds_read_b128 v[156:159], v186 offset:3072
	ds_read_b128 v[172:175], v186 offset:4096
	ds_read_b128 v[176:179], v186 offset:5120
	ds_read_b128 v[188:191], v186 offset:6144
	ds_read_b128 v[192:195], v186 offset:7168
	global_load_lds_dwordx4 v[180:181], off
	v_lshl_add_u64 v[180:181], s[48:49], 0, v[166:167]
	s_add_i32 m0, s11, 0xe000
	s_nop 0
	global_load_lds_dwordx4 v[180:181], off
	s_waitcnt lgkmcnt(8)
	s_barrier
	s_waitcnt lgkmcnt(0)
	s_waitcnt lgkmcnt(0)
	v_mfma_f32_16x16x32_bf16 v[140:143], v[48:51], v[144:147], v[140:143]
	v_mfma_f32_16x16x32_bf16 v[136:139], v[56:59], v[144:147], v[136:139]
	v_mfma_f32_16x16x32_bf16 v[124:127], v[48:51], v[152:155], v[124:127]
	v_mfma_f32_16x16x32_bf16 v[120:123], v[56:59], v[152:155], v[120:123]
	v_mfma_f32_16x16x32_bf16 v[108:111], v[48:51], v[172:175], v[108:111]
	v_mfma_f32_16x16x32_bf16 v[104:107], v[56:59], v[172:175], v[104:107]
	v_mfma_f32_16x16x32_bf16 v[92:95], v[48:51], v[188:191], v[92:95]
	v_mfma_f32_16x16x32_bf16 v[88:91], v[56:59], v[188:191], v[88:91]
	v_mfma_f32_16x16x32_bf16 v[140:143], v[52:55], v[148:151], v[140:143]
	v_mfma_f32_16x16x32_bf16 v[136:139], v[60:63], v[148:151], v[136:139]
	v_mfma_f32_16x16x32_bf16 v[124:127], v[52:55], v[156:159], v[124:127]
	v_mfma_f32_16x16x32_bf16 v[120:123], v[60:63], v[156:159], v[120:123]
	v_mfma_f32_16x16x32_bf16 v[108:111], v[52:55], v[176:179], v[108:111]
	v_mfma_f32_16x16x32_bf16 v[104:107], v[60:63], v[176:179], v[104:107]
	v_mfma_f32_16x16x32_bf16 v[92:95], v[52:55], v[192:195], v[92:95]
	v_mfma_f32_16x16x32_bf16 v[88:91], v[60:63], v[192:195], v[88:91]
	s_barrier
	s_add_i32 s47, s19, s10
	v_lshl_add_u64 v[180:181], s[52:53], 0, v[160:161]
	s_mov_b32 m0, s47
	ds_read_b128 v[196:199], v187
	ds_read_b128 v[200:203], v187 offset:1024
	ds_read_b128 v[204:207], v187 offset:2048
	ds_read_b128 v[208:211], v187 offset:3072
	global_load_lds_dwordx4 v[180:181], off
	v_lshl_add_u64 v[212:213], s[52:53], 0, v[162:163]
	s_add_i32 m0, s47, 0x2000
	s_nop 0
	global_load_lds_dwordx4 v[212:213], off
	s_barrier
	s_waitcnt lgkmcnt(0)
	s_waitcnt lgkmcnt(0)
	v_mfma_f32_16x16x32_bf16 v[132:135], v[196:199], v[144:147], v[132:135]
	v_mfma_f32_16x16x32_bf16 v[128:131], v[204:207], v[144:147], v[128:131]
	v_mfma_f32_16x16x32_bf16 v[116:119], v[196:199], v[152:155], v[116:119]
	v_mfma_f32_16x16x32_bf16 v[112:115], v[204:207], v[152:155], v[112:115]
	v_mfma_f32_16x16x32_bf16 v[100:103], v[196:199], v[172:175], v[100:103]
	v_mfma_f32_16x16x32_bf16 v[96:99], v[204:207], v[172:175], v[96:99]
	v_mfma_f32_16x16x32_bf16 v[84:87], v[196:199], v[188:191], v[84:87]
	v_mfma_f32_16x16x32_bf16 v[80:83], v[204:207], v[188:191], v[80:83]
	v_mfma_f32_16x16x32_bf16 v[132:135], v[200:203], v[148:151], v[132:135]
	v_mfma_f32_16x16x32_bf16 v[128:131], v[208:211], v[148:151], v[128:131]
	v_mfma_f32_16x16x32_bf16 v[116:119], v[200:203], v[156:159], v[116:119]
	v_mfma_f32_16x16x32_bf16 v[112:115], v[208:211], v[156:159], v[112:115]
	v_mfma_f32_16x16x32_bf16 v[100:103], v[200:203], v[176:179], v[100:103]
	v_mfma_f32_16x16x32_bf16 v[96:99], v[208:211], v[176:179], v[96:99]
	v_mfma_f32_16x16x32_bf16 v[84:87], v[200:203], v[192:195], v[84:87]
	v_mfma_f32_16x16x32_bf16 v[80:83], v[208:211], v[192:195], v[80:83]
	s_mov_b32 m0, s11
	v_lshl_add_u64 v[214:215], s[54:55], 0, v[160:161]
	s_barrier
	ds_read_b128 v[144:147], v186 offset:16384
	ds_read_b128 v[148:151], v186 offset:17408
	ds_read_b128 v[152:155], v186 offset:18432
	ds_read_b128 v[156:159], v186 offset:19456
	ds_read_b128 v[172:175], v186 offset:20480
	ds_read_b128 v[176:179], v186 offset:21504
	ds_read_b128 v[188:191], v186 offset:22528
	ds_read_b128 v[192:195], v186 offset:23552
	global_load_lds_dwordx4 v[214:215], off
	v_lshl_add_u64 v[216:217], s[54:55], 0, v[162:163]
	s_mov_b32 m0, s12
	s_nop 0
	global_load_lds_dwordx4 v[216:217], off
	s_barrier
	s_waitcnt lgkmcnt(0)
	s_waitcnt lgkmcnt(0)
	v_mfma_f32_16x16x32_bf16 v[76:79], v[48:51], v[144:147], v[76:79]
	v_mfma_f32_16x16x32_bf16 v[72:75], v[56:59], v[144:147], v[72:75]
	v_mfma_f32_16x16x32_bf16 v[44:47], v[48:51], v[152:155], v[44:47]
	v_mfma_f32_16x16x32_bf16 v[40:43], v[56:59], v[152:155], v[40:43]
	v_mfma_f32_16x16x32_bf16 v[28:31], v[48:51], v[172:175], v[28:31]
	v_mfma_f32_16x16x32_bf16 v[24:27], v[56:59], v[172:175], v[24:27]
	v_mfma_f32_16x16x32_bf16 v[12:15], v[48:51], v[188:191], v[12:15]
	v_mfma_f32_16x16x32_bf16 v[8:11], v[56:59], v[188:191], v[8:11]
	v_mfma_f32_16x16x32_bf16 v[76:79], v[52:55], v[148:151], v[76:79]
	v_mfma_f32_16x16x32_bf16 v[72:75], v[60:63], v[148:151], v[72:75]
	v_mfma_f32_16x16x32_bf16 v[44:47], v[52:55], v[156:159], v[44:47]
	v_mfma_f32_16x16x32_bf16 v[40:43], v[60:63], v[156:159], v[40:43]
	v_mfma_f32_16x16x32_bf16 v[28:31], v[52:55], v[176:179], v[28:31]
	v_mfma_f32_16x16x32_bf16 v[24:27], v[60:63], v[176:179], v[24:27]
	v_mfma_f32_16x16x32_bf16 v[12:15], v[52:55], v[192:195], v[12:15]
	v_mfma_f32_16x16x32_bf16 v[8:11], v[60:63], v[192:195], v[8:11]
	s_barrier
	s_add_u32 s50, s52, 0x40000
	s_addc_u32 s51, s53, 0
	s_add_i32 s47, s20, s10
	v_lshl_add_u64 v[48:49], s[50:51], 0, v[160:161]
	s_mov_b32 m0, s47
	s_nop 0
	global_load_lds_dwordx4 v[48:49], off
	v_lshl_add_u64 v[48:49], s[50:51], 0, v[162:163]
	s_add_i32 m0, s47, 0x2000
	s_nop 0
	global_load_lds_dwordx4 v[48:49], off
	s_waitcnt vmcnt(6)
	s_barrier
	v_mfma_f32_16x16x32_bf16 v[36:39], v[196:199], v[152:155], v[36:39]
	v_mfma_f32_16x16x32_bf16 v[32:35], v[204:207], v[152:155], v[32:35]
	v_mfma_f32_16x16x32_bf16 v[20:23], v[196:199], v[172:175], v[20:23]
	v_mfma_f32_16x16x32_bf16 v[16:19], v[204:207], v[172:175], v[16:19]
	v_mfma_f32_16x16x32_bf16 v[4:7], v[196:199], v[188:191], v[4:7]
	v_mfma_f32_16x16x32_bf16 v[0:3], v[204:207], v[188:191], v[0:3]
	v_mfma_f32_16x16x32_bf16 v[48:51], v[196:199], v[144:147], v[68:71]
	v_mfma_f32_16x16x32_bf16 v[52:55], v[204:207], v[144:147], v[64:67]
	v_mfma_f32_16x16x32_bf16 v[36:39], v[200:203], v[156:159], v[36:39]
	v_mfma_f32_16x16x32_bf16 v[32:35], v[208:211], v[156:159], v[32:35]
	v_mfma_f32_16x16x32_bf16 v[20:23], v[200:203], v[176:179], v[20:23]
	v_mfma_f32_16x16x32_bf16 v[16:19], v[208:211], v[176:179], v[16:19]
	v_mfma_f32_16x16x32_bf16 v[4:7], v[200:203], v[192:195], v[4:7]
	v_mfma_f32_16x16x32_bf16 v[0:3], v[208:211], v[192:195], v[0:3]
	v_mfma_f32_16x16x32_bf16 v[48:51], v[200:203], v[148:151], v[48:51]
	v_mfma_f32_16x16x32_bf16 v[52:55], v[208:211], v[148:151], v[52:55]
	s_add_i32 s47, 0, 0x18000
	v_add_u32_e32 v68, s47, v183
	s_barrier
	ds_read_b128 v[56:59], v68
	ds_read_b128 v[60:63], v68 offset:1024
	ds_read_b128 v[64:67], v68 offset:2048
	ds_read_b128 v[68:71], v68 offset:3072
	s_add_u32 s50, s54, 0x40000
	s_addc_u32 s51, s55, 0
	s_mov_b32 m0, s13
	v_lshl_add_u64 v[196:197], s[50:51], 0, v[160:161]
	ds_read_b128 v[144:147], v186 offset:32768
	ds_read_b128 v[148:151], v186 offset:33792
	ds_read_b128 v[152:155], v186 offset:34816
	ds_read_b128 v[156:159], v186 offset:35840
	ds_read_b128 v[172:175], v186 offset:36864
	ds_read_b128 v[176:179], v186 offset:37888
	ds_read_b128 v[188:191], v186 offset:38912
	ds_read_b128 v[192:195], v186 offset:39936
	global_load_lds_dwordx4 v[196:197], off
	v_lshl_add_u64 v[196:197], s[50:51], 0, v[162:163]
	s_mov_b32 m0, s14
	s_nop 0
	global_load_lds_dwordx4 v[196:197], off
	s_waitcnt lgkmcnt(8)
	s_barrier
	s_waitcnt lgkmcnt(0)
	s_waitcnt lgkmcnt(0)
	v_mfma_f32_16x16x32_bf16 v[140:143], v[56:59], v[144:147], v[140:143]
	v_mfma_f32_16x16x32_bf16 v[136:139], v[64:67], v[144:147], v[136:139]
	v_mfma_f32_16x16x32_bf16 v[124:127], v[56:59], v[152:155], v[124:127]
	v_mfma_f32_16x16x32_bf16 v[120:123], v[64:67], v[152:155], v[120:123]
	v_mfma_f32_16x16x32_bf16 v[108:111], v[56:59], v[172:175], v[108:111]
	v_mfma_f32_16x16x32_bf16 v[104:107], v[64:67], v[172:175], v[104:107]
	v_mfma_f32_16x16x32_bf16 v[92:95], v[56:59], v[188:191], v[92:95]
	v_mfma_f32_16x16x32_bf16 v[88:91], v[64:67], v[188:191], v[88:91]
	v_mfma_f32_16x16x32_bf16 v[140:143], v[60:63], v[148:151], v[140:143]
	v_mfma_f32_16x16x32_bf16 v[136:139], v[68:71], v[148:151], v[136:139]
	v_mfma_f32_16x16x32_bf16 v[124:127], v[60:63], v[156:159], v[124:127]
	v_mfma_f32_16x16x32_bf16 v[120:123], v[68:71], v[156:159], v[120:123]
	v_mfma_f32_16x16x32_bf16 v[108:111], v[60:63], v[176:179], v[108:111]
	v_mfma_f32_16x16x32_bf16 v[104:107], v[68:71], v[176:179], v[104:107]
	v_mfma_f32_16x16x32_bf16 v[92:95], v[60:63], v[192:195], v[92:95]
	v_mfma_f32_16x16x32_bf16 v[88:91], v[68:71], v[192:195], v[88:91]
	s_barrier
	s_add_i32 s54, 0, 0x1c000
	s_add_i32 s47, s47, s10
	v_add_u32_e32 v208, s54, v183
	v_lshl_add_u64 v[180:181], v[180:181], 0, s[28:29]
	s_mov_b32 m0, s47
	ds_read_b128 v[196:199], v208
	ds_read_b128 v[200:203], v208 offset:1024
	ds_read_b128 v[204:207], v208 offset:2048
	ds_read_b128 v[208:211], v208 offset:3072
	global_load_lds_dwordx4 v[180:181], off
	v_lshl_add_u64 v[180:181], v[212:213], 0, s[28:29]
	s_add_i32 m0, s47, 0x2000
	s_nop 0
	global_load_lds_dwordx4 v[180:181], off
	s_barrier
	s_waitcnt lgkmcnt(0)
	s_waitcnt lgkmcnt(0)
	v_mfma_f32_16x16x32_bf16 v[132:135], v[196:199], v[144:147], v[132:135]
	v_mfma_f32_16x16x32_bf16 v[128:131], v[204:207], v[144:147], v[128:131]
	v_mfma_f32_16x16x32_bf16 v[116:119], v[196:199], v[152:155], v[116:119]
	v_mfma_f32_16x16x32_bf16 v[112:115], v[204:207], v[152:155], v[112:115]
	v_mfma_f32_16x16x32_bf16 v[100:103], v[196:199], v[172:175], v[100:103]
	v_mfma_f32_16x16x32_bf16 v[96:99], v[204:207], v[172:175], v[96:99]
	v_mfma_f32_16x16x32_bf16 v[84:87], v[196:199], v[188:191], v[84:87]
	v_mfma_f32_16x16x32_bf16 v[80:83], v[204:207], v[188:191], v[80:83]
	v_mfma_f32_16x16x32_bf16 v[132:135], v[200:203], v[148:151], v[132:135]
	v_mfma_f32_16x16x32_bf16 v[128:131], v[208:211], v[148:151], v[128:131]
	v_mfma_f32_16x16x32_bf16 v[116:119], v[200:203], v[156:159], v[116:119]
	v_mfma_f32_16x16x32_bf16 v[112:115], v[208:211], v[156:159], v[112:115]
	v_mfma_f32_16x16x32_bf16 v[100:103], v[200:203], v[176:179], v[100:103]
	v_mfma_f32_16x16x32_bf16 v[96:99], v[208:211], v[176:179], v[96:99]
	v_mfma_f32_16x16x32_bf16 v[84:87], v[200:203], v[192:195], v[84:87]
	v_mfma_f32_16x16x32_bf16 v[80:83], v[208:211], v[192:195], v[80:83]
	s_mov_b32 m0, s16
	v_lshl_add_u64 v[180:181], v[214:215], 0, s[28:29]
	s_barrier
	ds_read_b128 v[144:147], v186 offset:49152
	ds_read_b128 v[148:151], v186 offset:50176
	ds_read_b128 v[152:155], v186 offset:51200
	ds_read_b128 v[156:159], v186 offset:52224
	ds_read_b128 v[172:175], v186 offset:53248
	ds_read_b128 v[176:179], v186 offset:54272
	ds_read_b128 v[188:191], v186 offset:55296
	ds_read_b128 v[192:195], v186 offset:56320
	global_load_lds_dwordx4 v[180:181], off
	v_lshl_add_u64 v[180:181], v[216:217], 0, s[28:29]
	s_mov_b32 m0, s17
	s_nop 0
	global_load_lds_dwordx4 v[180:181], off
	s_barrier
	s_waitcnt lgkmcnt(0)
	s_waitcnt lgkmcnt(0)
	v_mfma_f32_16x16x32_bf16 v[76:79], v[56:59], v[144:147], v[76:79]
	v_mfma_f32_16x16x32_bf16 v[72:75], v[64:67], v[144:147], v[72:75]
	v_mfma_f32_16x16x32_bf16 v[44:47], v[56:59], v[152:155], v[44:47]
	v_mfma_f32_16x16x32_bf16 v[40:43], v[64:67], v[152:155], v[40:43]
	v_mfma_f32_16x16x32_bf16 v[28:31], v[56:59], v[172:175], v[28:31]
	v_mfma_f32_16x16x32_bf16 v[24:27], v[64:67], v[172:175], v[24:27]
	v_mfma_f32_16x16x32_bf16 v[12:15], v[56:59], v[188:191], v[12:15]
	v_mfma_f32_16x16x32_bf16 v[8:11], v[64:67], v[188:191], v[8:11]
	v_mfma_f32_16x16x32_bf16 v[76:79], v[60:63], v[148:151], v[76:79]
	v_mfma_f32_16x16x32_bf16 v[72:75], v[68:71], v[148:151], v[72:75]
	v_mfma_f32_16x16x32_bf16 v[44:47], v[60:63], v[156:159], v[44:47]
	v_mfma_f32_16x16x32_bf16 v[40:43], v[68:71], v[156:159], v[40:43]
	v_mfma_f32_16x16x32_bf16 v[28:31], v[60:63], v[176:179], v[28:31]
	v_mfma_f32_16x16x32_bf16 v[24:27], v[68:71], v[176:179], v[24:27]
	v_mfma_f32_16x16x32_bf16 v[12:15], v[60:63], v[192:195], v[12:15]
	v_mfma_f32_16x16x32_bf16 v[8:11], v[68:71], v[192:195], v[8:11]
	s_barrier
	s_add_u32 s50, s52, 0x40080
	s_addc_u32 s51, s53, 0
	s_add_i32 s47, s54, s10
	v_lshl_add_u64 v[56:57], s[50:51], 0, v[160:161]
	s_mov_b32 m0, s47
	s_nop 0
	global_load_lds_dwordx4 v[56:57], off
	v_lshl_add_u64 v[56:57], s[50:51], 0, v[162:163]
	s_add_i32 m0, s47, 0x2000
	s_nop 0
	global_load_lds_dwordx4 v[56:57], off
	s_waitcnt vmcnt(6)
	s_barrier
	v_mfma_f32_16x16x32_bf16 v[48:51], v[196:199], v[144:147], v[48:51]
	v_mfma_f32_16x16x32_bf16 v[68:71], v[200:203], v[148:151], v[48:51]
	v_mfma_f32_16x16x32_bf16 v[48:51], v[204:207], v[144:147], v[52:55]
	v_mfma_f32_16x16x32_bf16 v[36:39], v[196:199], v[152:155], v[36:39]
	v_mfma_f32_16x16x32_bf16 v[32:35], v[204:207], v[152:155], v[32:35]
	v_mfma_f32_16x16x32_bf16 v[20:23], v[196:199], v[172:175], v[20:23]
	v_mfma_f32_16x16x32_bf16 v[16:19], v[204:207], v[172:175], v[16:19]
	v_mfma_f32_16x16x32_bf16 v[4:7], v[196:199], v[188:191], v[4:7]
	v_mfma_f32_16x16x32_bf16 v[0:3], v[204:207], v[188:191], v[0:3]
	v_mfma_f32_16x16x32_bf16 v[64:67], v[208:211], v[148:151], v[48:51]
	v_mfma_f32_16x16x32_bf16 v[36:39], v[200:203], v[156:159], v[36:39]
	v_mfma_f32_16x16x32_bf16 v[32:35], v[208:211], v[156:159], v[32:35]
	v_mfma_f32_16x16x32_bf16 v[20:23], v[200:203], v[176:179], v[20:23]
	v_mfma_f32_16x16x32_bf16 v[16:19], v[208:211], v[176:179], v[16:19]
	v_mfma_f32_16x16x32_bf16 v[4:7], v[200:203], v[192:195], v[4:7]
	v_mfma_f32_16x16x32_bf16 v[0:3], v[208:211], v[192:195], v[0:3]
	s_add_i32 s35, s35, 2
	s_add_u32 s48, s48, 0x100
	s_addc_u32 s49, s49, 0
	s_add_u32 s31, s31, 0x100
	s_addc_u32 s33, s33, 0
	s_cmp_gt_u32 s35, 13
	s_barrier
	s_cbranch_scc0 .LBB0_618
	v_and_b32_e32 v145, 64, v229
	v_xor_b32_e32 v144, 16, v229
	v_add_u32_e32 v145, 64, v145
	v_cmp_lt_i32_e32 vcc, v144, v145
	v_lshl_or_b32 v172, s46, 8, v184
	v_ashrrev_i32_e32 v173, 31, v172
	v_cndmask_b32_e32 v144, v229, v144, vcc
	v_lshl_add_u32 v174, s2, 8, v182
	v_lshlrev_b32_e32 v189, 2, v144
	v_xor_b32_e32 v144, 32, v229
	v_lshlrev_b64 v[206:207], 2, v[172:173]
	v_cmp_lt_i32_e32 vcc, v144, v145
	v_ashrrev_i32_e32 v175, 31, v174
	v_lshl_add_u64 v[176:177], s[44:45], 0, v[206:207]
	v_cndmask_b32_e32 v144, v229, v144, vcc
	v_lshlrev_b64 v[208:209], 12, v[174:175]
	v_lshl_add_u64 v[56:57], s[56:57], 0, v[206:207]
	v_lshlrev_b32_e32 v188, 2, v144
	v_lshl_add_u64 v[144:145], v[176:177], 0, v[208:209]
	global_load_dwordx4 v[52:55], v[56:57], off offset:16
	global_load_dwordx4 v[60:63], v[56:57], off
	global_load_dwordx4 v[48:51], v[56:57], off offset:144
	s_nop 0
	global_load_dwordx4 v[56:59], v[56:57], off offset:128
	s_nop 0
	global_load_dwordx4 v[190:193], v[144:145], off offset:16
	global_load_dwordx4 v[194:197], v[144:145], off
	global_load_dwordx4 v[198:201], v[144:145], off offset:144
	global_load_dwordx4 v[202:205], v[144:145], off offset:128
	v_or_b32_e32 v178, 16, v174
	v_ashrrev_i32_e32 v179, 31, v178
	v_lshlrev_b64 v[180:181], 12, v[178:179]
	v_lshl_add_u64 v[148:149], v[176:177], 0, v[180:181]
	global_load_dwordx4 v[152:155], v[148:149], off offset:16
	global_load_dwordx4 v[156:159], v[148:149], off
	global_load_dwordx4 v[144:147], v[148:149], off offset:144
	s_nop 0
	global_load_dwordx4 v[148:151], v[148:149], off offset:128
	s_waitcnt vmcnt(0)
	v_pk_add_f32 v[136:137], v[136:137], v[190:191]
	v_pk_add_f32 v[194:195], v[140:141], v[194:195]
	v_pk_add_f32 v[198:199], v[128:129], v[198:199]
	v_lshl_add_u64 v[128:129], s[78:79], 0, v[208:209]
	v_pk_add_f32 v[196:197], v[142:143], v[196:197]
	v_pk_mul_f32 v[212:213], v[194:195], v[194:195]
	v_pk_add_f32 v[190:191], v[132:133], v[202:203]
	v_lshl_add_u64 v[128:129], v[128:129], 0, v[206:207]
	v_pk_mul_f32 v[210:211], v[196:197], v[196:197]
	v_pk_add_f32 v[138:139], v[138:139], v[192:193]
	v_pk_add_f32 v[192:193], v[134:135], v[204:205]
	v_pk_mul_f32 v[204:205], v[190:191], v[190:191]
	v_pk_add_f32 v[200:201], v[130:131], v[200:201]
	global_store_dwordx4 v[128:129], v[194:197], off nt
	global_store_dwordx4 v[128:129], v[136:139], off offset:16 nt
	global_store_dwordx4 v[128:129], v[190:193], off offset:128 nt
	global_store_dwordx4 v[128:129], v[198:201], off offset:144 nt
	v_pk_mul_f32 v[134:135], v[56:57], v[190:191]
	v_add_f32_e32 v190, v212, v213
	v_add_f32_e32 v190, v210, v190
	v_pk_mul_f32 v[216:217], v[136:137], v[136:137]
	v_add_f32_e32 v190, v211, v190
	v_add_f32_e32 v190, v216, v190
	v_pk_mul_f32 v[214:215], v[138:139], v[138:139]
	v_add_f32_e32 v190, v217, v190
	v_add_f32_e32 v190, v214, v190
	v_add_f32_e32 v190, v215, v190
	v_add_f32_e32 v190, v204, v190
	v_pk_mul_f32 v[202:203], v[192:193], v[192:193]
	v_add_f32_e32 v190, v205, v190
	v_add_f32_e32 v190, v202, v190
	v_pk_mul_f32 v[220:221], v[198:199], v[198:199]
	v_add_f32_e32 v190, v203, v190
	v_add_f32_e32 v190, v220, v190
	v_pk_mul_f32 v[218:219], v[200:201], v[200:201]
	v_add_f32_e32 v190, v221, v190
	v_add_f32_e32 v190, v218, v190
	v_pk_mul_f32 v[128:129], v[62:63], v[196:197]
	v_add_f32_e32 v196, v219, v190
	v_lshlrev_b64 v[190:191], 11, v[174:175]
	v_pk_mul_f32 v[142:143], v[60:61], v[194:195]
	v_pk_mul_f32 v[130:131], v[52:53], v[136:137]
	v_pk_mul_f32 v[132:133], v[54:55], v[138:139]
	v_lshl_add_u64 v[190:191], s[24:25], 0, v[190:191]
	v_pk_mul_f32 v[136:137], v[58:59], v[192:193]
	v_pk_mul_f32 v[138:139], v[48:49], v[198:199]
	v_pk_mul_f32 v[140:141], v[50:51], v[200:201]
	v_lshl_add_u64 v[194:195], v[172:173], 1, v[190:191]
	v_cvt_pk_bf16_f32 v190, v142, v143
	v_cvt_pk_bf16_f32 v191, v128, v129
	v_cvt_pk_bf16_f32 v192, v130, v131
	v_cvt_pk_bf16_f32 v193, v132, v133
	v_cvt_pk_bf16_f32 v128, v134, v135
	v_cvt_pk_bf16_f32 v129, v136, v137
	v_cvt_pk_bf16_f32 v130, v138, v139
	v_cvt_pk_bf16_f32 v131, v140, v141
	global_store_dwordx4 v[194:195], v[190:193], off nt
	global_store_dwordx4 v[194:195], v[128:131], off offset:64 nt
	ds_bpermute_b32 v128, v189, v196
	s_waitcnt lgkmcnt(0)
	v_add_f32_e32 v128, v196, v128
	ds_bpermute_b32 v129, v188, v128
	s_and_saveexec_b64 s[2:3], s[36:37]
	s_cbranch_execz .LBB0_621
	v_lshl_add_u64 v[130:131], v[174:175], 2, s[26:27]
	s_waitcnt lgkmcnt(0)
	v_add_f32_e32 v128, v128, v129
	global_atomic_add_f32 v[130:131], v128, off

.LBB0_703:
	ds_read_b128 v[44:47], v236
	ds_read_b128 v[48:51], v236 offset:1024
	ds_read_b128 v[52:55], v236 offset:2048
	ds_read_b128 v[56:59], v236 offset:3072
	s_add_u32 s0, vcc_lo, 0xfffc0080
	s_addc_u32 s1, vcc_hi, -1
	s_cmp_eq_u32 s59, 12
	s_cselect_b32 s91, s22, s1
	s_cselect_b32 s90, s23, s0
	s_cselect_b32 s1, s3, s57
	s_cselect_b32 s0, s51, s55
	v_lshl_add_u64 v[190:191], vcc, 0, v[166:167]
	s_add_i32 m0, s12, 0xc000
	ds_read_b128 v[68:71], v237
	ds_read_b128 v[72:75], v237 offset:1024
	ds_read_b128 v[76:79], v237 offset:2048
	ds_read_b128 v[80:83], v237 offset:3072
	ds_read_b128 v[174:177], v237 offset:4096
	ds_read_b128 v[178:181], v237 offset:5120
	ds_read_b128 v[182:185], v237 offset:6144
	ds_read_b128 v[186:189], v237 offset:7168
	global_load_lds_dwordx4 v[190:191], off
	v_lshl_add_u64 v[190:191], vcc, 0, v[168:169]
	s_add_i32 m0, s12, 0xe000
	s_nop 0
	global_load_lds_dwordx4 v[190:191], off
	s_waitcnt lgkmcnt(8)
	s_barrier
	s_waitcnt lgkmcnt(0)
	s_waitcnt lgkmcnt(0)
	v_mfma_f32_16x16x32_bf16 v[156:159], v[44:47], v[68:71], v[156:159]
	v_mfma_f32_16x16x32_bf16 v[132:135], v[52:55], v[68:71], v[132:135]
	v_mfma_f32_16x16x32_bf16 v[152:155], v[44:47], v[76:79], v[152:155]
	v_mfma_f32_16x16x32_bf16 v[128:131], v[52:55], v[76:79], v[128:131]
	v_mfma_f32_16x16x32_bf16 v[140:143], v[44:47], v[174:177], v[140:143]
	v_mfma_f32_16x16x32_bf16 v[104:107], v[52:55], v[174:177], v[104:107]
	v_mfma_f32_16x16x32_bf16 v[144:147], v[44:47], v[182:185], v[144:147]
	v_mfma_f32_16x16x32_bf16 v[108:111], v[52:55], v[182:185], v[108:111]
	v_mfma_f32_16x16x32_bf16 v[156:159], v[48:51], v[72:75], v[156:159]
	v_mfma_f32_16x16x32_bf16 v[132:135], v[56:59], v[72:75], v[132:135]
	v_mfma_f32_16x16x32_bf16 v[152:155], v[48:51], v[80:83], v[152:155]
	v_mfma_f32_16x16x32_bf16 v[128:131], v[56:59], v[80:83], v[128:131]
	v_mfma_f32_16x16x32_bf16 v[140:143], v[48:51], v[178:181], v[140:143]
	v_mfma_f32_16x16x32_bf16 v[104:107], v[56:59], v[178:181], v[104:107]
	v_mfma_f32_16x16x32_bf16 v[144:147], v[48:51], v[186:189], v[144:147]
	v_mfma_f32_16x16x32_bf16 v[108:111], v[56:59], v[186:189], v[108:111]
	s_barrier
	s_add_i32 s60, s20, s11
	v_lshl_add_u64 v[214:215], s[0:1], 0, v[160:161]
	s_mov_b32 m0, s60
	ds_read_b128 v[190:193], v238
	ds_read_b128 v[194:197], v238 offset:1024
	ds_read_b128 v[198:201], v238 offset:2048
	ds_read_b128 v[202:205], v238 offset:3072
	global_load_lds_dwordx4 v[214:215], off
	v_lshl_add_u64 v[216:217], s[0:1], 0, v[162:163]
	s_add_i32 m0, s60, 0x2000
	s_nop 0
	global_load_lds_dwordx4 v[216:217], off
	s_barrier
	s_waitcnt lgkmcnt(0)
	s_waitcnt lgkmcnt(0)
	v_mfma_f32_16x16x32_bf16 v[148:151], v[190:193], v[68:71], v[148:151]
	v_mfma_f32_16x16x32_bf16 v[68:71], v[198:201], v[68:71], v[124:127]
	v_mfma_f32_16x16x32_bf16 v[148:151], v[194:197], v[72:75], v[148:151]
	v_mfma_f32_16x16x32_bf16 v[68:71], v[202:205], v[72:75], v[68:71]
	v_mfma_f32_16x16x32_bf16 v[72:75], v[190:193], v[76:79], v[120:123]
	v_mfma_f32_16x16x32_bf16 v[76:79], v[198:201], v[76:79], v[112:115]
	v_mfma_f32_16x16x32_bf16 v[100:103], v[198:201], v[174:177], v[100:103]
	v_mfma_f32_16x16x32_bf16 v[112:115], v[190:193], v[182:185], v[136:139]
	v_mfma_f32_16x16x32_bf16 v[96:99], v[198:201], v[182:185], v[96:99]
	v_mfma_f32_16x16x32_bf16 v[72:75], v[194:197], v[80:83], v[72:75]
	v_mfma_f32_16x16x32_bf16 v[76:79], v[202:205], v[80:83], v[76:79]
	v_mfma_f32_16x16x32_bf16 v[80:83], v[190:193], v[174:177], v[116:119]
	v_mfma_f32_16x16x32_bf16 v[100:103], v[202:205], v[178:181], v[100:103]
	v_mfma_f32_16x16x32_bf16 v[136:139], v[194:197], v[186:189], v[112:115]
	v_mfma_f32_16x16x32_bf16 v[96:99], v[202:205], v[186:189], v[96:99]
	v_mfma_f32_16x16x32_bf16 v[80:83], v[194:197], v[178:181], v[80:83]
	s_mov_b32 m0, s12
	v_lshl_add_u64 v[218:219], s[90:91], 0, v[160:161]
	s_barrier
	ds_read_b128 v[112:115], v237 offset:16384
	ds_read_b128 v[116:119], v237 offset:17408
	ds_read_b128 v[120:123], v237 offset:18432
	ds_read_b128 v[124:127], v237 offset:19456
	ds_read_b128 v[174:177], v237 offset:20480
	ds_read_b128 v[178:181], v237 offset:21504
	ds_read_b128 v[182:185], v237 offset:22528
	ds_read_b128 v[186:189], v237 offset:23552
	global_load_lds_dwordx4 v[218:219], off
	v_lshl_add_u64 v[220:221], s[90:91], 0, v[162:163]
	s_mov_b32 m0, s13
	s_nop 0
	global_load_lds_dwordx4 v[220:221], off
	s_barrier
	s_waitcnt lgkmcnt(0)
	s_waitcnt lgkmcnt(0)
	v_mfma_f32_16x16x32_bf16 v[92:95], v[44:47], v[112:115], v[92:95]
	v_mfma_f32_16x16x32_bf16 v[40:43], v[52:55], v[112:115], v[40:43]
	v_mfma_f32_16x16x32_bf16 v[88:91], v[44:47], v[120:123], v[88:91]
	v_mfma_f32_16x16x32_bf16 v[36:39], v[52:55], v[120:123], v[36:39]
	v_mfma_f32_16x16x32_bf16 v[60:63], v[44:47], v[174:177], v[60:63]
	v_mfma_f32_16x16x32_bf16 v[8:11], v[52:55], v[174:177], v[8:11]
	v_mfma_f32_16x16x32_bf16 v[16:19], v[52:55], v[182:185], v[16:19]
	v_mfma_f32_16x16x32_bf16 v[92:95], v[48:51], v[116:119], v[92:95]
	v_mfma_f32_16x16x32_bf16 v[40:43], v[56:59], v[116:119], v[40:43]
	v_mfma_f32_16x16x32_bf16 v[88:91], v[48:51], v[124:127], v[88:91]
	v_mfma_f32_16x16x32_bf16 v[36:39], v[56:59], v[124:127], v[36:39]
	v_mfma_f32_16x16x32_bf16 v[60:63], v[48:51], v[178:181], v[60:63]
	v_mfma_f32_16x16x32_bf16 v[8:11], v[56:59], v[178:181], v[8:11]
	v_mfma_f32_16x16x32_bf16 v[44:47], v[44:47], v[182:185], v[64:67]
	v_mfma_f32_16x16x32_bf16 v[16:19], v[56:59], v[186:189], v[16:19]
	v_mfma_f32_16x16x32_bf16 v[44:47], v[48:51], v[186:189], v[44:47]
	s_barrier
	s_add_u32 s60, s0, 0x40000
	s_addc_u32 s61, s1, 0
	s_add_i32 s63, s21, s11
	v_lshl_add_u64 v[48:49], s[60:61], 0, v[160:161]
	s_mov_b32 m0, s63
	s_nop 0
	global_load_lds_dwordx4 v[48:49], off
	v_lshl_add_u64 v[48:49], s[60:61], 0, v[162:163]
	s_add_i32 m0, s63, 0x2000
	s_nop 0
	global_load_lds_dwordx4 v[48:49], off
	s_waitcnt vmcnt(6)
	s_barrier
	v_mfma_f32_16x16x32_bf16 v[28:31], v[198:201], v[112:115], v[28:31]
	v_mfma_f32_16x16x32_bf16 v[24:27], v[190:193], v[120:123], v[24:27]
	v_mfma_f32_16x16x32_bf16 v[12:15], v[198:201], v[120:123], v[12:15]
	v_mfma_f32_16x16x32_bf16 v[20:23], v[190:193], v[174:177], v[20:23]
	v_mfma_f32_16x16x32_bf16 v[4:7], v[198:201], v[174:177], v[4:7]
	v_mfma_f32_16x16x32_bf16 v[32:35], v[190:193], v[182:185], v[32:35]
	v_mfma_f32_16x16x32_bf16 v[0:3], v[198:201], v[182:185], v[0:3]
	v_mfma_f32_16x16x32_bf16 v[48:51], v[190:193], v[112:115], v[84:87]
	v_mfma_f32_16x16x32_bf16 v[28:31], v[202:205], v[116:119], v[28:31]
	v_mfma_f32_16x16x32_bf16 v[24:27], v[194:197], v[124:127], v[24:27]
	v_mfma_f32_16x16x32_bf16 v[12:15], v[202:205], v[124:127], v[12:15]
	v_mfma_f32_16x16x32_bf16 v[20:23], v[194:197], v[178:181], v[20:23]
	v_mfma_f32_16x16x32_bf16 v[4:7], v[202:205], v[178:181], v[4:7]
	v_mfma_f32_16x16x32_bf16 v[32:35], v[194:197], v[186:189], v[32:35]
	v_mfma_f32_16x16x32_bf16 v[0:3], v[202:205], v[186:189], v[0:3]
	v_mfma_f32_16x16x32_bf16 v[48:51], v[194:197], v[116:119], v[48:51]
	s_add_i32 s63, 0, 0x18000
	v_add_u32_e32 v64, s63, v232
	s_barrier
	ds_read_b128 v[52:55], v64
	ds_read_b128 v[56:59], v64 offset:1024
	ds_read_b128 v[84:87], v64 offset:2048
	ds_read_b128 v[174:177], v64 offset:3072
	s_add_u32 s60, s90, 0x40000
	s_addc_u32 s61, s91, 0
	s_mov_b32 m0, s14
	v_lshl_add_u64 v[120:121], s[60:61], 0, v[160:161]
	ds_read_b128 v[64:67], v237 offset:32768
	ds_read_b128 v[112:115], v237 offset:33792
	ds_read_b128 v[116:119], v237 offset:34816
	ds_read_b128 v[178:181], v237 offset:35840
	ds_read_b128 v[182:185], v237 offset:36864
	ds_read_b128 v[186:189], v237 offset:37888
	ds_read_b128 v[190:193], v237 offset:38912
	ds_read_b128 v[194:197], v237 offset:39936
	global_load_lds_dwordx4 v[120:121], off
	v_lshl_add_u64 v[120:121], s[60:61], 0, v[162:163]
	s_mov_b32 m0, s15
	s_nop 0
	global_load_lds_dwordx4 v[120:121], off
	s_waitcnt lgkmcnt(8)
	s_barrier
	s_waitcnt lgkmcnt(0)
	s_waitcnt lgkmcnt(0)
	v_mfma_f32_16x16x32_bf16 v[120:123], v[52:55], v[64:67], v[156:159]
	v_mfma_f32_16x16x32_bf16 v[156:159], v[56:59], v[112:115], v[120:123]
	v_mfma_f32_16x16x32_bf16 v[120:123], v[84:87], v[64:67], v[132:135]
	v_mfma_f32_16x16x32_bf16 v[132:135], v[174:177], v[112:115], v[120:123]
	v_mfma_f32_16x16x32_bf16 v[120:123], v[52:55], v[116:119], v[152:155]
	v_mfma_f32_16x16x32_bf16 v[152:155], v[56:59], v[178:181], v[120:123]
	v_mfma_f32_16x16x32_bf16 v[120:123], v[84:87], v[116:119], v[128:131]
	v_mfma_f32_16x16x32_bf16 v[128:131], v[174:177], v[178:181], v[120:123]
	v_mfma_f32_16x16x32_bf16 v[120:123], v[52:55], v[182:185], v[140:143]
	v_mfma_f32_16x16x32_bf16 v[140:143], v[56:59], v[186:189], v[120:123]
	v_mfma_f32_16x16x32_bf16 v[104:107], v[84:87], v[182:185], v[104:107]
	v_mfma_f32_16x16x32_bf16 v[120:123], v[52:55], v[190:193], v[144:147]
	v_mfma_f32_16x16x32_bf16 v[108:111], v[84:87], v[190:193], v[108:111]
	v_mfma_f32_16x16x32_bf16 v[104:107], v[174:177], v[186:189], v[104:107]
	v_mfma_f32_16x16x32_bf16 v[144:147], v[56:59], v[194:197], v[120:123]
	v_mfma_f32_16x16x32_bf16 v[108:111], v[174:177], v[194:197], v[108:111]
	s_barrier
	s_add_i32 s60, 0, 0x1c000
	s_nop 0
	v_add_u32_e32 v120, s60, v232
	s_add_i32 s61, s63, s11
	ds_read_b128 v[198:201], v120
	ds_read_b128 v[202:205], v120 offset:1024
	ds_read_b128 v[206:209], v120 offset:2048
	ds_read_b128 v[210:213], v120 offset:3072
	v_lshl_add_u64 v[120:121], v[214:215], 0, s[52:53]
	s_mov_b32 m0, s61
	s_nop 0
	global_load_lds_dwordx4 v[120:121], off
	v_lshl_add_u64 v[120:121], v[216:217], 0, s[52:53]
	s_add_i32 m0, s61, 0x2000
	s_nop 0
	global_load_lds_dwordx4 v[120:121], off
	s_barrier
	s_waitcnt lgkmcnt(0)
	s_waitcnt lgkmcnt(0)
	v_mfma_f32_16x16x32_bf16 v[120:123], v[198:201], v[64:67], v[148:151]
	v_mfma_f32_16x16x32_bf16 v[64:67], v[206:209], v[64:67], v[68:71]
	v_mfma_f32_16x16x32_bf16 v[124:127], v[210:213], v[112:115], v[64:67]
	v_mfma_f32_16x16x32_bf16 v[64:67], v[198:201], v[116:119], v[72:75]
	v_mfma_f32_16x16x32_bf16 v[148:151], v[202:205], v[112:115], v[120:123]
	v_mfma_f32_16x16x32_bf16 v[120:123], v[202:205], v[178:181], v[64:67]
	v_mfma_f32_16x16x32_bf16 v[64:67], v[206:209], v[116:119], v[76:79]
	v_mfma_f32_16x16x32_bf16 v[112:115], v[210:213], v[178:181], v[64:67]
	v_mfma_f32_16x16x32_bf16 v[64:67], v[198:201], v[182:185], v[80:83]
	v_mfma_f32_16x16x32_bf16 v[116:119], v[202:205], v[186:189], v[64:67]
	v_mfma_f32_16x16x32_bf16 v[64:67], v[206:209], v[182:185], v[100:103]
	v_mfma_f32_16x16x32_bf16 v[100:103], v[210:213], v[186:189], v[64:67]
	v_mfma_f32_16x16x32_bf16 v[64:67], v[198:201], v[190:193], v[136:139]
	v_mfma_f32_16x16x32_bf16 v[136:139], v[202:205], v[194:197], v[64:67]
	v_mfma_f32_16x16x32_bf16 v[64:67], v[206:209], v[190:193], v[96:99]
	v_mfma_f32_16x16x32_bf16 v[96:99], v[210:213], v[194:197], v[64:67]
	s_mov_b32 m0, s17
	s_nop 4
	v_lshl_add_u64 v[64:65], v[218:219], 0, s[52:53]
	s_barrier
	ds_read_b128 v[68:71], v237 offset:49152
	ds_read_b128 v[72:75], v237 offset:50176
	ds_read_b128 v[76:79], v237 offset:51200
	ds_read_b128 v[80:83], v237 offset:52224
	ds_read_b128 v[178:181], v237 offset:53248
	ds_read_b128 v[182:185], v237 offset:54272
	ds_read_b128 v[186:189], v237 offset:55296
	ds_read_b128 v[190:193], v237 offset:56320
	global_load_lds_dwordx4 v[64:65], off
	v_lshl_add_u64 v[64:65], v[220:221], 0, s[52:53]
	s_mov_b32 m0, s18
	s_nop 0
	global_load_lds_dwordx4 v[64:65], off
	s_barrier
	s_waitcnt lgkmcnt(0)
	s_waitcnt lgkmcnt(0)
	v_mfma_f32_16x16x32_bf16 v[64:67], v[52:55], v[68:71], v[92:95]
	v_mfma_f32_16x16x32_bf16 v[92:95], v[56:59], v[72:75], v[64:67]
	v_mfma_f32_16x16x32_bf16 v[40:43], v[84:87], v[68:71], v[40:43]
	v_mfma_f32_16x16x32_bf16 v[64:67], v[52:55], v[76:79], v[88:91]
	v_mfma_f32_16x16x32_bf16 v[36:39], v[84:87], v[76:79], v[36:39]
	v_mfma_f32_16x16x32_bf16 v[60:63], v[52:55], v[178:181], v[60:63]
	v_mfma_f32_16x16x32_bf16 v[8:11], v[84:87], v[178:181], v[8:11]
	v_mfma_f32_16x16x32_bf16 v[44:47], v[52:55], v[186:189], v[44:47]
	v_mfma_f32_16x16x32_bf16 v[16:19], v[84:87], v[186:189], v[16:19]
	v_mfma_f32_16x16x32_bf16 v[40:43], v[174:177], v[72:75], v[40:43]
	v_mfma_f32_16x16x32_bf16 v[88:91], v[56:59], v[80:83], v[64:67]
	v_mfma_f32_16x16x32_bf16 v[36:39], v[174:177], v[80:83], v[36:39]
	v_mfma_f32_16x16x32_bf16 v[60:63], v[56:59], v[182:185], v[60:63]
	v_mfma_f32_16x16x32_bf16 v[8:11], v[174:177], v[182:185], v[8:11]
	v_mfma_f32_16x16x32_bf16 v[64:67], v[56:59], v[190:193], v[44:47]
	v_mfma_f32_16x16x32_bf16 v[16:19], v[174:177], v[190:193], v[16:19]
	s_barrier
	s_add_u32 s0, s0, 0x40080
	s_addc_u32 s1, s1, 0
	s_add_i32 s60, s60, s11
	v_lshl_add_u64 v[44:45], s[0:1], 0, v[160:161]
	s_mov_b32 m0, s60
	s_nop 0
	global_load_lds_dwordx4 v[44:45], off
	v_lshl_add_u64 v[44:45], s[0:1], 0, v[162:163]
	s_add_i32 m0, s60, 0x2000
	s_nop 0
	global_load_lds_dwordx4 v[44:45], off
	s_waitcnt vmcnt(6)
	s_barrier
	v_mfma_f32_16x16x32_bf16 v[44:47], v[198:201], v[68:71], v[48:51]
	v_mfma_f32_16x16x32_bf16 v[28:31], v[206:209], v[68:71], v[28:31]
	v_mfma_f32_16x16x32_bf16 v[24:27], v[198:201], v[76:79], v[24:27]
	v_mfma_f32_16x16x32_bf16 v[12:15], v[206:209], v[76:79], v[12:15]
	v_mfma_f32_16x16x32_bf16 v[20:23], v[198:201], v[178:181], v[20:23]
	v_mfma_f32_16x16x32_bf16 v[4:7], v[206:209], v[178:181], v[4:7]
	v_mfma_f32_16x16x32_bf16 v[32:35], v[198:201], v[186:189], v[32:35]
	v_mfma_f32_16x16x32_bf16 v[0:3], v[206:209], v[186:189], v[0:3]
	v_mfma_f32_16x16x32_bf16 v[84:87], v[202:205], v[72:75], v[44:47]
	v_mfma_f32_16x16x32_bf16 v[28:31], v[210:213], v[72:75], v[28:31]
	v_mfma_f32_16x16x32_bf16 v[24:27], v[202:205], v[80:83], v[24:27]
	v_mfma_f32_16x16x32_bf16 v[12:15], v[210:213], v[80:83], v[12:15]
	v_mfma_f32_16x16x32_bf16 v[20:23], v[202:205], v[182:185], v[20:23]
	v_mfma_f32_16x16x32_bf16 v[4:7], v[210:213], v[182:185], v[4:7]
	v_mfma_f32_16x16x32_bf16 v[32:35], v[202:205], v[190:193], v[32:35]
	v_mfma_f32_16x16x32_bf16 v[0:3], v[210:213], v[190:193], v[0:3]
	s_add_i32 s59, s59, 2
	s_add_u32 vcc_lo, vcc_lo, 0x100
	s_addc_u32 vcc_hi, vcc_hi, 0
	s_add_u32 s55, s55, 0x100
	s_addc_u32 s57, s57, 0
	s_cmp_gt_u32 s59, 13
	s_barrier
	s_cbranch_scc0 .LBB0_703
	v_lshl_add_u32 v164, s84, 8, v231
	v_lshl_add_u64 v[44:45], v[164:165], 2, s[34:35]
	global_load_dword v184, v[44:45], off
	v_or_b32_e32 v182, 16, v164
	v_mov_b32_e32 v183, v165
	v_lshl_add_u64 v[44:45], v[182:183], 2, s[34:35]
	global_load_dword v186, v[44:45], off
	v_or_b32_e32 v44, 32, v164
	v_mov_b32_e32 v45, v165
	v_lshl_add_u64 v[44:45], v[44:45], 2, s[34:35]
	v_or_b32_e32 v180, 48, v164
	v_mov_b32_e32 v181, v165
	global_load_dword v200, v[44:45], off
	v_lshl_add_u64 v[44:45], v[180:181], 2, s[34:35]
	v_add_u32_e32 v178, 0x80, v164
	v_mov_b32_e32 v179, v165
	global_load_dword v185, v[44:45], off
	v_lshl_add_u64 v[44:45], v[178:179], 2, s[34:35]
	v_add_u32_e32 v174, 0x90, v164
	v_mov_b32_e32 v175, v165
	global_load_dword v183, v[44:45], off
	v_lshl_add_u64 v[44:45], v[174:175], 2, s[34:35]
	global_load_dword v181, v[44:45], off
	v_add_u32_e32 v44, 0xa0, v164
	v_mov_b32_e32 v45, v165
	v_lshl_add_u64 v[44:45], v[44:45], 2, s[34:35]
	global_load_dword v175, v[44:45], off
	v_add_u32_e32 v44, 0xb0, v164
	v_mov_b32_e32 v45, v165
	v_lshl_or_b32 v176, s88, 7, v235
	v_lshl_add_u64 v[44:45], v[44:45], 2, s[34:35]
	v_ashrrev_i32_e32 v177, 31, v176
	v_readlane_b32 s44, v254, 1
	global_load_dword v179, v[44:45], off
	v_lshlrev_b64 v[44:45], 2, v[176:177]
	v_readlane_b32 s48, v254, 5
	v_readlane_b32 s49, v254, 6
	v_readlane_b32 s50, v254, 7
	v_readlane_b32 s51, v254, 8
	v_lshl_add_u64 v[48:49], s[48:49], 0, v[44:45]
	v_lshl_add_u64 v[52:53], s[96:97], 0, v[44:45]
	v_lshl_add_u64 v[56:57], s[86:87], 0, v[44:45]
	v_lshl_add_u64 v[80:81], s[50:51], 0, v[44:45]
	global_load_dwordx4 v[44:47], v[48:49], off offset:16
	global_load_dwordx4 v[68:71], v[48:49], off
	s_nop 0
	global_load_dwordx4 v[48:51], v[52:53], off offset:16
	global_load_dwordx4 v[72:75], v[52:53], off
	s_nop 0
	global_load_dwordx4 v[52:55], v[56:57], off offset:16
	global_load_dwordx4 v[76:79], v[56:57], off
	s_nop 0
	global_load_dwordx4 v[56:59], v[80:81], off offset:16
	s_nop 0
	global_load_dwordx4 v[80:83], v[80:81], off
	v_mov_b32_e32 v190, 0
	v_mov_b32_e32 v192, 0
	v_mov_b32_e32 v191, 0
	v_mov_b32_e32 v193, 0
	v_mov_b32_e32 v196, 0
	s_lshl_b32 s3, s84, 2
	v_mov_b32_e32 v198, 0
	s_add_i32 s3, s3, s10
	v_mov_b32_e32 v197, 0
	s_mul_i32 s51, s3, 6
	v_mov_b32_e32 v199, 0
	v_readlane_b32 s45, v254, 2
	v_readlane_b32 s46, v254, 3
	v_readlane_b32 s47, v254, 4
	s_waitcnt vmcnt(0)
	v_fmamk_f32 v177, v184, 0x3a800000, v239
	v_cmp_gt_f32_e32 vcc, s33, v177
	v_mul_f32_e32 v184, 0x4b800000, v177
	s_nop 0
	v_cndmask_b32_e32 v177, v177, v184, vcc
	v_rsq_f32_e32 v177, v177
	s_nop 0
	v_mul_f32_e32 v184, 0x45800000, v177
	v_cndmask_b32_e32 v188, v177, v184, vcc
	v_fmamk_f32 v177, v186, 0x3a800000, v239
	v_cmp_gt_f32_e32 vcc, s33, v177
	v_mul_f32_e32 v184, 0x4b800000, v177
	v_pk_mul_f32 v[186:187], v[156:157], v[188:189] op_sel_hi:[1,0]
	v_cndmask_b32_e32 v177, v177, v184, vcc
	v_rsq_f32_e32 v177, v177
	v_cndmask_b32_e64 v156, v186, 0, s[38:39]
	v_pk_mul_f32 v[194:195], v[158:159], v[188:189] op_sel_hi:[1,0]
	v_mul_f32_e32 v184, 0x45800000, v177
	v_cndmask_b32_e32 v184, v177, v184, vcc
	v_mov_b32_dpp v190, v156 row_ror:1 row_mask:0xf bank_mask:0xf
	v_pk_mul_f32 v[156:157], v[152:153], v[184:185] op_sel_hi:[1,0]
	v_pk_mul_f32 v[158:159], v[154:155], v[184:185] op_sel_hi:[1,0]
	v_cndmask_b32_e64 v152, v186, v156, s[42:43]
	v_add_u32_e32 v155, s51, v234
	s_nop 0
	v_mov_b32_dpp v192, v152 row_ror:15 row_mask:0xf bank_mask:0xf
	v_cndmask_b32_e64 v152, v187, 0, s[38:39]
	s_nop 1
	v_mov_b32_dpp v191, v152 row_ror:1 row_mask:0xf bank_mask:0xf
	v_cndmask_b32_e64 v152, v187, v157, s[42:43]
	s_nop 1
	v_mov_b32_dpp v193, v152 row_ror:15 row_mask:0xf bank_mask:0xf
	v_cndmask_b32_e64 v152, v194, 0, s[38:39]
	s_nop 1
	v_mov_b32_dpp v196, v152 row_ror:1 row_mask:0xf bank_mask:0xf
	v_cndmask_b32_e64 v152, v194, v158, s[42:43]
	s_nop 1
	v_mov_b32_dpp v198, v152 row_ror:15 row_mask:0xf bank_mask:0xf
	v_cndmask_b32_e64 v152, v195, 0, s[38:39]
	s_nop 1
	v_mov_b32_dpp v197, v152 row_ror:1 row_mask:0xf bank_mask:0xf
	v_cndmask_b32_e64 v152, v195, v159, s[42:43]
	s_nop 1
	v_mov_b32_dpp v199, v152 row_ror:15 row_mask:0xf bank_mask:0xf
	s_and_saveexec_b64 s[0:1], s[70:71]
	s_cbranch_execz .LBB0_706
	v_mad_u64_u32 v[202:203], s[22:23], v155, s65, v[176:177]
	v_mov_b32_e32 v203, v165
	v_cvt_pk_bf16_f32 v152, v186, v187
	v_cvt_pk_bf16_f32 v153, v194, v195
	v_lshl_add_u64 v[202:203], v[202:203], 1, s[30:31]
	global_store_dwordx2 v[202:203], v[152:153], off

.LBB0_888:
	ds_read_b128 v[140:143], v149
	ds_read_b128 v[152:155], v149 offset:1024
	ds_read_b128 v[156:159], v149 offset:2048
	ds_read_b128 v[160:163], v149 offset:3072
	s_add_u32 s10, s2, 0x100
	s_addc_u32 s11, s3, 0
	s_cmp_eq_u32 s39, 40
	s_cselect_b32 s15, s7, s11
	s_cselect_b32 s14, s6, s10
	s_cselect_b32 s13, s5, s38
	s_cselect_b32 s12, s4, s37
	v_lshl_add_u64 v[144:145], s[2:3], 0, v[132:133]
	s_add_i32 m0, s23, 0xc000
	ds_read_b128 v[164:167], v150
	ds_read_b128 v[168:171], v150 offset:1024
	ds_read_b128 v[172:175], v150 offset:2048
	ds_read_b128 v[176:179], v150 offset:3072
	ds_read_b128 v[180:183], v150 offset:4096
	ds_read_b128 v[184:187], v150 offset:5120
	ds_read_b128 v[188:191], v150 offset:6144
	ds_read_b128 v[192:195], v150 offset:7168
	global_load_lds_dwordx4 v[144:145], off
	v_lshl_add_u64 v[144:145], s[2:3], 0, v[134:135]
	s_add_i32 m0, s23, 0xe000
	s_nop 0
	global_load_lds_dwordx4 v[144:145], off
	s_waitcnt lgkmcnt(8)
	s_barrier
	s_waitcnt lgkmcnt(0)
	s_waitcnt lgkmcnt(0)
	v_mfma_f32_16x16x32_bf16 v[124:127], v[140:143], v[164:167], v[124:127]
	v_mfma_f32_16x16x32_bf16 v[120:123], v[156:159], v[164:167], v[120:123]
	v_mfma_f32_16x16x32_bf16 v[116:119], v[140:143], v[172:175], v[116:119]
	v_mfma_f32_16x16x32_bf16 v[112:115], v[156:159], v[172:175], v[112:115]
	v_mfma_f32_16x16x32_bf16 v[92:95], v[140:143], v[180:183], v[92:95]
	v_mfma_f32_16x16x32_bf16 v[88:91], v[156:159], v[180:183], v[88:91]
	v_mfma_f32_16x16x32_bf16 v[84:87], v[140:143], v[188:191], v[84:87]
	v_mfma_f32_16x16x32_bf16 v[80:83], v[156:159], v[188:191], v[80:83]
	v_mfma_f32_16x16x32_bf16 v[124:127], v[152:155], v[168:171], v[124:127]
	v_mfma_f32_16x16x32_bf16 v[120:123], v[160:163], v[168:171], v[120:123]
	v_mfma_f32_16x16x32_bf16 v[116:119], v[152:155], v[176:179], v[116:119]
	v_mfma_f32_16x16x32_bf16 v[112:115], v[160:163], v[176:179], v[112:115]
	v_mfma_f32_16x16x32_bf16 v[92:95], v[152:155], v[184:187], v[92:95]
	v_mfma_f32_16x16x32_bf16 v[88:91], v[160:163], v[184:187], v[88:91]
	v_mfma_f32_16x16x32_bf16 v[84:87], v[152:155], v[192:195], v[84:87]
	v_mfma_f32_16x16x32_bf16 v[80:83], v[160:163], v[192:195], v[80:83]
	s_barrier
	s_add_i32 s2, s30, s22
	v_lshl_add_u64 v[144:145], s[12:13], 0, v[128:129]
	s_mov_b32 m0, s2
	ds_read_b128 v[196:199], v151
	ds_read_b128 v[200:203], v151 offset:1024
	ds_read_b128 v[204:207], v151 offset:2048
	ds_read_b128 v[208:211], v151 offset:3072
	global_load_lds_dwordx4 v[144:145], off
	v_lshl_add_u64 v[212:213], s[12:13], 0, v[130:131]
	s_add_i32 m0, s2, 0x2000
	s_nop 0
	global_load_lds_dwordx4 v[212:213], off
	s_barrier
	s_waitcnt lgkmcnt(0)
	s_waitcnt lgkmcnt(0)
	v_mfma_f32_16x16x32_bf16 v[108:111], v[196:199], v[164:167], v[108:111]
	v_mfma_f32_16x16x32_bf16 v[104:107], v[204:207], v[164:167], v[104:107]
	v_mfma_f32_16x16x32_bf16 v[100:103], v[196:199], v[172:175], v[100:103]
	v_mfma_f32_16x16x32_bf16 v[96:99], v[204:207], v[172:175], v[96:99]
	v_mfma_f32_16x16x32_bf16 v[76:79], v[196:199], v[180:183], v[76:79]
	v_mfma_f32_16x16x32_bf16 v[72:75], v[204:207], v[180:183], v[72:75]
	v_mfma_f32_16x16x32_bf16 v[68:71], v[196:199], v[188:191], v[68:71]
	v_mfma_f32_16x16x32_bf16 v[64:67], v[204:207], v[188:191], v[64:67]
	v_mfma_f32_16x16x32_bf16 v[108:111], v[200:203], v[168:171], v[108:111]
	v_mfma_f32_16x16x32_bf16 v[104:107], v[208:211], v[168:171], v[104:107]
	v_mfma_f32_16x16x32_bf16 v[100:103], v[200:203], v[176:179], v[100:103]
	v_mfma_f32_16x16x32_bf16 v[96:99], v[208:211], v[176:179], v[96:99]
	v_mfma_f32_16x16x32_bf16 v[76:79], v[200:203], v[184:187], v[76:79]
	v_mfma_f32_16x16x32_bf16 v[72:75], v[208:211], v[184:187], v[72:75]
	v_mfma_f32_16x16x32_bf16 v[68:71], v[200:203], v[192:195], v[68:71]
	v_mfma_f32_16x16x32_bf16 v[64:67], v[208:211], v[192:195], v[64:67]
	s_mov_b32 m0, s23
	v_lshl_add_u64 v[214:215], s[14:15], 0, v[128:129]
	s_barrier
	ds_read_b128 v[164:167], v150 offset:16384
	ds_read_b128 v[168:171], v150 offset:17408
	ds_read_b128 v[172:175], v150 offset:18432
	ds_read_b128 v[176:179], v150 offset:19456
	ds_read_b128 v[180:183], v150 offset:20480
	ds_read_b128 v[184:187], v150 offset:21504
	ds_read_b128 v[188:191], v150 offset:22528
	ds_read_b128 v[192:195], v150 offset:23552
	global_load_lds_dwordx4 v[214:215], off
	v_lshl_add_u64 v[216:217], s[14:15], 0, v[130:131]
	s_mov_b32 m0, s24
	s_nop 0
	global_load_lds_dwordx4 v[216:217], off
	s_barrier
	s_waitcnt lgkmcnt(0)
	s_waitcnt lgkmcnt(0)
	v_mfma_f32_16x16x32_bf16 v[60:63], v[140:143], v[164:167], v[60:63]
	v_mfma_f32_16x16x32_bf16 v[56:59], v[156:159], v[164:167], v[56:59]
	v_mfma_f32_16x16x32_bf16 v[52:55], v[140:143], v[172:175], v[52:55]
	v_mfma_f32_16x16x32_bf16 v[48:51], v[156:159], v[172:175], v[48:51]
	v_mfma_f32_16x16x32_bf16 v[28:31], v[140:143], v[180:183], v[28:31]
	v_mfma_f32_16x16x32_bf16 v[24:27], v[156:159], v[180:183], v[24:27]
	v_mfma_f32_16x16x32_bf16 v[16:19], v[140:143], v[188:191], v[16:19]
	v_mfma_f32_16x16x32_bf16 v[8:11], v[156:159], v[188:191], v[8:11]
	v_mfma_f32_16x16x32_bf16 v[60:63], v[152:155], v[168:171], v[60:63]
	v_mfma_f32_16x16x32_bf16 v[56:59], v[160:163], v[168:171], v[56:59]
	v_mfma_f32_16x16x32_bf16 v[52:55], v[152:155], v[176:179], v[52:55]
	v_mfma_f32_16x16x32_bf16 v[48:51], v[160:163], v[176:179], v[48:51]
	v_mfma_f32_16x16x32_bf16 v[28:31], v[152:155], v[184:187], v[28:31]
	v_mfma_f32_16x16x32_bf16 v[24:27], v[160:163], v[184:187], v[24:27]
	v_mfma_f32_16x16x32_bf16 v[16:19], v[152:155], v[192:195], v[16:19]
	v_mfma_f32_16x16x32_bf16 v[8:11], v[160:163], v[192:195], v[8:11]
	s_barrier
	s_add_u32 s2, s12, 0xb0000
	s_addc_u32 s3, s13, 0
	s_add_i32 s40, s31, s22
	v_lshl_add_u64 v[140:141], s[2:3], 0, v[128:129]
	s_mov_b32 m0, s40
	s_nop 0
	global_load_lds_dwordx4 v[140:141], off
	v_lshl_add_u64 v[140:141], s[2:3], 0, v[130:131]
	s_add_i32 m0, s40, 0x2000
	s_nop 0
	global_load_lds_dwordx4 v[140:141], off
	s_waitcnt vmcnt(6)
	s_barrier
	v_mfma_f32_16x16x32_bf16 v[44:47], v[196:199], v[164:167], v[44:47]
	v_mfma_f32_16x16x32_bf16 v[40:43], v[204:207], v[164:167], v[40:43]
	v_mfma_f32_16x16x32_bf16 v[36:39], v[196:199], v[172:175], v[36:39]
	v_mfma_f32_16x16x32_bf16 v[32:35], v[204:207], v[172:175], v[32:35]
	v_mfma_f32_16x16x32_bf16 v[20:23], v[196:199], v[180:183], v[20:23]
	v_mfma_f32_16x16x32_bf16 v[12:15], v[204:207], v[180:183], v[12:15]
	v_mfma_f32_16x16x32_bf16 v[4:7], v[196:199], v[188:191], v[4:7]
	v_mfma_f32_16x16x32_bf16 v[0:3], v[204:207], v[188:191], v[0:3]
	v_mfma_f32_16x16x32_bf16 v[44:47], v[200:203], v[168:171], v[44:47]
	v_mfma_f32_16x16x32_bf16 v[40:43], v[208:211], v[168:171], v[40:43]
	v_mfma_f32_16x16x32_bf16 v[36:39], v[200:203], v[176:179], v[36:39]
	v_mfma_f32_16x16x32_bf16 v[32:35], v[208:211], v[176:179], v[32:35]
	v_mfma_f32_16x16x32_bf16 v[20:23], v[200:203], v[184:187], v[20:23]
	v_mfma_f32_16x16x32_bf16 v[12:15], v[208:211], v[184:187], v[12:15]
	v_mfma_f32_16x16x32_bf16 v[4:7], v[200:203], v[192:195], v[4:7]
	v_mfma_f32_16x16x32_bf16 v[0:3], v[208:211], v[192:195], v[0:3]
	s_add_i32 s40, 0, 0x18000
	v_add_u32_e32 v160, s40, v147
	s_barrier
	ds_read_b128 v[140:143], v160
	ds_read_b128 v[152:155], v160 offset:1024
	ds_read_b128 v[156:159], v160 offset:2048
	ds_read_b128 v[160:163], v160 offset:3072
	s_add_u32 s2, s14, 0xb0000
	s_addc_u32 s3, s15, 0
	s_mov_b32 m0, s25
	v_lshl_add_u64 v[196:197], s[2:3], 0, v[128:129]
	ds_read_b128 v[164:167], v150 offset:32768
	ds_read_b128 v[168:171], v150 offset:33792
	ds_read_b128 v[172:175], v150 offset:34816
	ds_read_b128 v[176:179], v150 offset:35840
	ds_read_b128 v[180:183], v150 offset:36864
	ds_read_b128 v[184:187], v150 offset:37888
	ds_read_b128 v[188:191], v150 offset:38912
	ds_read_b128 v[192:195], v150 offset:39936
	global_load_lds_dwordx4 v[196:197], off
	v_lshl_add_u64 v[196:197], s[2:3], 0, v[130:131]
	s_mov_b32 m0, s26
	s_nop 0
	global_load_lds_dwordx4 v[196:197], off
	s_waitcnt lgkmcnt(8)
	s_barrier
	s_waitcnt lgkmcnt(0)
	s_waitcnt lgkmcnt(0)
	v_mfma_f32_16x16x32_bf16 v[124:127], v[140:143], v[164:167], v[124:127]
	v_mfma_f32_16x16x32_bf16 v[120:123], v[156:159], v[164:167], v[120:123]
	v_mfma_f32_16x16x32_bf16 v[116:119], v[140:143], v[172:175], v[116:119]
	v_mfma_f32_16x16x32_bf16 v[112:115], v[156:159], v[172:175], v[112:115]
	v_mfma_f32_16x16x32_bf16 v[92:95], v[140:143], v[180:183], v[92:95]
	v_mfma_f32_16x16x32_bf16 v[88:91], v[156:159], v[180:183], v[88:91]
	v_mfma_f32_16x16x32_bf16 v[84:87], v[140:143], v[188:191], v[84:87]
	v_mfma_f32_16x16x32_bf16 v[80:83], v[156:159], v[188:191], v[80:83]
	v_mfma_f32_16x16x32_bf16 v[124:127], v[152:155], v[168:171], v[124:127]
	v_mfma_f32_16x16x32_bf16 v[120:123], v[160:163], v[168:171], v[120:123]
	v_mfma_f32_16x16x32_bf16 v[116:119], v[152:155], v[176:179], v[116:119]
	v_mfma_f32_16x16x32_bf16 v[112:115], v[160:163], v[176:179], v[112:115]
	v_mfma_f32_16x16x32_bf16 v[92:95], v[152:155], v[184:187], v[92:95]
	v_mfma_f32_16x16x32_bf16 v[88:91], v[160:163], v[184:187], v[88:91]
	v_mfma_f32_16x16x32_bf16 v[84:87], v[152:155], v[192:195], v[84:87]
	v_mfma_f32_16x16x32_bf16 v[80:83], v[160:163], v[192:195], v[80:83]
	s_barrier
	s_add_i32 s14, 0, 0x1c000
	s_add_i32 s2, s40, s22
	v_add_u32_e32 v208, s14, v147
	v_lshl_add_u64 v[144:145], v[144:145], 0, s[8:9]
	s_mov_b32 m0, s2
	ds_read_b128 v[196:199], v208
	ds_read_b128 v[200:203], v208 offset:1024
	ds_read_b128 v[204:207], v208 offset:2048
	ds_read_b128 v[208:211], v208 offset:3072
	global_load_lds_dwordx4 v[144:145], off
	v_lshl_add_u64 v[144:145], v[212:213], 0, s[8:9]
	s_add_i32 m0, s2, 0x2000
	s_nop 0
	global_load_lds_dwordx4 v[144:145], off
	s_barrier
	s_waitcnt lgkmcnt(0)
	s_waitcnt lgkmcnt(0)
	v_mfma_f32_16x16x32_bf16 v[108:111], v[196:199], v[164:167], v[108:111]
	v_mfma_f32_16x16x32_bf16 v[104:107], v[204:207], v[164:167], v[104:107]
	v_mfma_f32_16x16x32_bf16 v[100:103], v[196:199], v[172:175], v[100:103]
	v_mfma_f32_16x16x32_bf16 v[96:99], v[204:207], v[172:175], v[96:99]
	v_mfma_f32_16x16x32_bf16 v[76:79], v[196:199], v[180:183], v[76:79]
	v_mfma_f32_16x16x32_bf16 v[72:75], v[204:207], v[180:183], v[72:75]
	v_mfma_f32_16x16x32_bf16 v[68:71], v[196:199], v[188:191], v[68:71]
	v_mfma_f32_16x16x32_bf16 v[64:67], v[204:207], v[188:191], v[64:67]
	v_mfma_f32_16x16x32_bf16 v[108:111], v[200:203], v[168:171], v[108:111]
	v_mfma_f32_16x16x32_bf16 v[104:107], v[208:211], v[168:171], v[104:107]
	v_mfma_f32_16x16x32_bf16 v[100:103], v[200:203], v[176:179], v[100:103]
	v_mfma_f32_16x16x32_bf16 v[96:99], v[208:211], v[176:179], v[96:99]
	v_mfma_f32_16x16x32_bf16 v[76:79], v[200:203], v[184:187], v[76:79]
	v_mfma_f32_16x16x32_bf16 v[72:75], v[208:211], v[184:187], v[72:75]
	v_mfma_f32_16x16x32_bf16 v[68:71], v[200:203], v[192:195], v[68:71]
	v_mfma_f32_16x16x32_bf16 v[64:67], v[208:211], v[192:195], v[64:67]
	s_mov_b32 m0, s28
	v_lshl_add_u64 v[144:145], v[214:215], 0, s[8:9]
	s_barrier
	ds_read_b128 v[164:167], v150 offset:49152
	ds_read_b128 v[168:171], v150 offset:50176
	ds_read_b128 v[172:175], v150 offset:51200
	ds_read_b128 v[176:179], v150 offset:52224
	ds_read_b128 v[180:183], v150 offset:53248
	ds_read_b128 v[184:187], v150 offset:54272
	ds_read_b128 v[188:191], v150 offset:55296
	ds_read_b128 v[192:195], v150 offset:56320
	global_load_lds_dwordx4 v[144:145], off
	v_lshl_add_u64 v[144:145], v[216:217], 0, s[8:9]
	s_mov_b32 m0, s29
	s_nop 0
	global_load_lds_dwordx4 v[144:145], off
	s_barrier
	s_waitcnt lgkmcnt(0)
	s_waitcnt lgkmcnt(0)
	v_mfma_f32_16x16x32_bf16 v[60:63], v[140:143], v[164:167], v[60:63]
	v_mfma_f32_16x16x32_bf16 v[56:59], v[156:159], v[164:167], v[56:59]
	v_mfma_f32_16x16x32_bf16 v[52:55], v[140:143], v[172:175], v[52:55]
	v_mfma_f32_16x16x32_bf16 v[48:51], v[156:159], v[172:175], v[48:51]
	v_mfma_f32_16x16x32_bf16 v[28:31], v[140:143], v[180:183], v[28:31]
	v_mfma_f32_16x16x32_bf16 v[24:27], v[156:159], v[180:183], v[24:27]
	v_mfma_f32_16x16x32_bf16 v[16:19], v[140:143], v[188:191], v[16:19]
	v_mfma_f32_16x16x32_bf16 v[8:11], v[156:159], v[188:191], v[8:11]
	v_mfma_f32_16x16x32_bf16 v[60:63], v[152:155], v[168:171], v[60:63]
	v_mfma_f32_16x16x32_bf16 v[56:59], v[160:163], v[168:171], v[56:59]
	v_mfma_f32_16x16x32_bf16 v[52:55], v[152:155], v[176:179], v[52:55]
	v_mfma_f32_16x16x32_bf16 v[48:51], v[160:163], v[176:179], v[48:51]
	v_mfma_f32_16x16x32_bf16 v[28:31], v[152:155], v[184:187], v[28:31]
	v_mfma_f32_16x16x32_bf16 v[24:27], v[160:163], v[184:187], v[24:27]
	v_mfma_f32_16x16x32_bf16 v[16:19], v[152:155], v[192:195], v[16:19]
	v_mfma_f32_16x16x32_bf16 v[8:11], v[160:163], v[192:195], v[8:11]
	s_barrier
	s_add_u32 s2, s12, 0xb0080
	s_addc_u32 s3, s13, 0
	s_add_i32 s12, s14, s22
	v_lshl_add_u64 v[140:141], s[2:3], 0, v[128:129]
	s_mov_b32 m0, s12
	s_nop 0
	global_load_lds_dwordx4 v[140:141], off
	v_lshl_add_u64 v[140:141], s[2:3], 0, v[130:131]
	s_add_i32 m0, s12, 0x2000
	s_nop 0
	global_load_lds_dwordx4 v[140:141], off
	s_waitcnt vmcnt(6)
	s_barrier
	v_mfma_f32_16x16x32_bf16 v[44:47], v[196:199], v[164:167], v[44:47]
	v_mfma_f32_16x16x32_bf16 v[40:43], v[204:207], v[164:167], v[40:43]
	v_mfma_f32_16x16x32_bf16 v[36:39], v[196:199], v[172:175], v[36:39]
	v_mfma_f32_16x16x32_bf16 v[32:35], v[204:207], v[172:175], v[32:35]
	v_mfma_f32_16x16x32_bf16 v[20:23], v[196:199], v[180:183], v[20:23]
	v_mfma_f32_16x16x32_bf16 v[12:15], v[204:207], v[180:183], v[12:15]
	v_mfma_f32_16x16x32_bf16 v[4:7], v[196:199], v[188:191], v[4:7]
	v_mfma_f32_16x16x32_bf16 v[0:3], v[204:207], v[188:191], v[0:3]
	v_mfma_f32_16x16x32_bf16 v[44:47], v[200:203], v[168:171], v[44:47]
	v_mfma_f32_16x16x32_bf16 v[40:43], v[208:211], v[168:171], v[40:43]
	v_mfma_f32_16x16x32_bf16 v[36:39], v[200:203], v[176:179], v[36:39]
	v_mfma_f32_16x16x32_bf16 v[32:35], v[208:211], v[176:179], v[32:35]
	v_mfma_f32_16x16x32_bf16 v[20:23], v[200:203], v[184:187], v[20:23]
	v_mfma_f32_16x16x32_bf16 v[12:15], v[208:211], v[184:187], v[12:15]
	v_mfma_f32_16x16x32_bf16 v[4:7], v[200:203], v[192:195], v[4:7]
	v_mfma_f32_16x16x32_bf16 v[0:3], v[208:211], v[192:195], v[0:3]
	s_add_i32 s39, s39, 2
	s_add_u32 s37, s37, 0x100
	s_addc_u32 s38, s38, 0
	s_cmp_gt_u32 s39, 41
	s_mov_b64 s[2:3], s[10:11]
	s_barrier
	s_cbranch_scc0 .LBB0_888
	v_lshl_or_b32 v140, s36, 8, v148
	v_lshl_add_u32 v144, s35, 8, v146
	v_ashrrev_i32_e32 v141, 31, v140
	v_lshlrev_b64 v[140:141], 2, v[140:141]
	v_ashrrev_i32_e32 v145, 31, v144
	v_lshl_add_u64 v[142:143], s[78:79], 0, v[140:141]
	v_lshlrev_b64 v[184:185], 12, v[144:145]
	v_lshl_add_u64 v[164:165], v[142:143], 0, v[184:185]
	v_or_b32_e32 v168, 16, v144
	global_load_dwordx4 v[152:155], v[164:165], off offset:16
	global_load_dwordx4 v[156:159], v[164:165], off
	global_load_dwordx4 v[160:163], v[164:165], off offset:144
	s_nop 0
	global_load_dwordx4 v[164:167], v[164:165], off offset:128
	v_ashrrev_i32_e32 v169, 31, v168
	v_lshlrev_b64 v[186:187], 12, v[168:169]
	v_lshl_add_u64 v[180:181], v[142:143], 0, v[186:187]
	global_load_dwordx4 v[168:171], v[180:181], off offset:16
	global_load_dwordx4 v[172:175], v[180:181], off
	global_load_dwordx4 v[176:179], v[180:181], off offset:144
	s_nop 0
	global_load_dwordx4 v[180:183], v[180:181], off offset:128
	s_and_b64 vcc, exec, s[0:1]
	s_mov_b32 s36, s34
	s_mov_b32 s35, s33
	s_mov_b64 s[10:11], s[4:5]
	s_mov_b64 s[2:3], s[6:7]
	s_waitcnt vmcnt(0)
	v_pk_add_f32 v[120:121], v[120:121], v[152:153]
	v_lshl_add_u64 v[152:153], s[78:79], 0, v[184:185]
	v_pk_add_f32 v[126:127], v[126:127], v[158:159]
	v_pk_add_f32 v[124:125], v[124:125], v[156:157]
	v_pk_add_f32 v[108:109], v[108:109], v[164:165]
	v_lshl_add_u64 v[152:153], v[152:153], 0, v[140:141]
	v_pk_add_f32 v[122:123], v[122:123], v[154:155]
	v_pk_add_f32 v[110:111], v[110:111], v[166:167]
	v_pk_add_f32 v[106:107], v[106:107], v[162:163]
	v_pk_add_f32 v[104:105], v[104:105], v[160:161]
	global_store_dwordx4 v[152:153], v[124:127], off nt
	global_store_dwordx4 v[152:153], v[120:123], off offset:16 nt
	global_store_dwordx4 v[152:153], v[108:111], off offset:128 nt
	global_store_dwordx4 v[152:153], v[104:107], off offset:144 nt
	v_pk_add_f32 v[96:97], v[96:97], v[176:177]
	v_pk_add_f32 v[108:109], v[112:113], v[168:169]
	v_lshl_add_u64 v[112:113], s[78:79], 0, v[186:187]
	v_pk_add_f32 v[106:107], v[118:119], v[174:175]
	v_pk_add_f32 v[104:105], v[116:117], v[172:173]
	v_lshl_add_u64 v[112:113], v[112:113], 0, v[140:141]
	v_pk_add_f32 v[110:111], v[114:115], v[170:171]
	v_pk_add_f32 v[102:103], v[102:103], v[182:183]
	v_pk_add_f32 v[100:101], v[100:101], v[180:181]
	v_pk_add_f32 v[98:99], v[98:99], v[178:179]
	global_store_dwordx4 v[112:113], v[104:107], off nt
	global_store_dwordx4 v[112:113], v[108:111], off offset:16 nt
	global_store_dwordx4 v[112:113], v[100:103], off offset:128 nt
	global_store_dwordx4 v[112:113], v[96:99], off offset:144 nt
	v_or_b32_e32 v112, 48, v144
	v_ashrrev_i32_e32 v113, 31, v112
	v_or_b32_e32 v96, 32, v144
	v_ashrrev_i32_e32 v97, 31, v96
	v_lshlrev_b64 v[152:153], 12, v[96:97]
	v_lshl_add_u64 v[108:109], v[142:143], 0, v[152:153]
	global_load_dwordx4 v[96:99], v[108:109], off offset:16
	global_load_dwordx4 v[100:103], v[108:109], off
	global_load_dwordx4 v[104:107], v[108:109], off offset:144
	s_nop 0
	global_load_dwordx4 v[108:111], v[108:109], off offset:128
	v_lshlrev_b64 v[154:155], 12, v[112:113]
	v_lshl_add_u64 v[124:125], v[142:143], 0, v[154:155]
	global_load_dwordx4 v[112:115], v[124:125], off offset:16
	global_load_dwordx4 v[116:119], v[124:125], off
	global_load_dwordx4 v[120:123], v[124:125], off offset:144
	s_nop 0
	global_load_dwordx4 v[124:127], v[124:125], off offset:128
	s_waitcnt vmcnt(0)
	v_pk_add_f32 v[88:89], v[88:89], v[96:97]
	v_lshl_add_u64 v[96:97], s[78:79], 0, v[152:153]
	v_pk_add_f32 v[94:95], v[94:95], v[102:103]
	v_pk_add_f32 v[92:93], v[92:93], v[100:101]
	v_pk_add_f32 v[76:77], v[76:77], v[108:109]
	v_lshl_add_u64 v[96:97], v[96:97], 0, v[140:141]
	v_pk_add_f32 v[90:91], v[90:91], v[98:99]
	v_pk_add_f32 v[78:79], v[78:79], v[110:111]
	v_pk_add_f32 v[74:75], v[74:75], v[106:107]
	v_pk_add_f32 v[72:73], v[72:73], v[104:105]
	global_store_dwordx4 v[96:97], v[92:95], off nt
	global_store_dwordx4 v[96:97], v[88:91], off offset:16 nt
	global_store_dwordx4 v[96:97], v[76:79], off offset:128 nt
	global_store_dwordx4 v[96:97], v[72:75], off offset:144 nt
	v_pk_add_f32 v[64:65], v[64:65], v[120:121]
	v_pk_add_f32 v[76:77], v[80:81], v[112:113]
	v_lshl_add_u64 v[80:81], s[78:79], 0, v[154:155]
	v_pk_add_f32 v[74:75], v[86:87], v[118:119]
	v_pk_add_f32 v[72:73], v[84:85], v[116:117]
	v_lshl_add_u64 v[80:81], v[80:81], 0, v[140:141]
	v_pk_add_f32 v[78:79], v[82:83], v[114:115]
	v_pk_add_f32 v[70:71], v[70:71], v[126:127]
	v_pk_add_f32 v[68:69], v[68:69], v[124:125]
	v_pk_add_f32 v[66:67], v[66:67], v[122:123]
	global_store_dwordx4 v[80:81], v[72:75], off nt
	global_store_dwordx4 v[80:81], v[76:79], off offset:16 nt
	global_store_dwordx4 v[80:81], v[68:71], off offset:128 nt
	global_store_dwordx4 v[80:81], v[64:67], off offset:144 nt
	s_nop 1
	v_add_u32_e32 v64, 0x80, v144
	v_ashrrev_i32_e32 v65, 31, v64
	v_lshlrev_b64 v[96:97], 12, v[64:65]
	v_lshl_add_u64 v[80:81], v[142:143], 0, v[96:97]
	global_load_dwordx4 v[64:67], v[80:81], off offset:16
	global_load_dwordx4 v[68:71], v[80:81], off
	global_load_dwordx4 v[72:75], v[80:81], off offset:144
	global_load_dwordx4 v[76:79], v[80:81], off offset:128
	v_add_u32_e32 v80, 0x90, v144
	v_ashrrev_i32_e32 v81, 31, v80
	v_lshlrev_b64 v[98:99], 12, v[80:81]
	v_lshl_add_u64 v[100:101], v[142:143], 0, v[98:99]
	global_load_dwordx4 v[80:83], v[100:101], off offset:16
	global_load_dwordx4 v[84:87], v[100:101], off
	global_load_dwordx4 v[88:91], v[100:101], off offset:144
	global_load_dwordx4 v[92:95], v[100:101], off offset:128
	s_waitcnt vmcnt(0)
	v_pk_add_f32 v[56:57], v[56:57], v[64:65]
	v_lshl_add_u64 v[64:65], s[78:79], 0, v[96:97]
	v_pk_add_f32 v[62:63], v[62:63], v[70:71]
	v_pk_add_f32 v[60:61], v[60:61], v[68:69]
	v_pk_add_f32 v[44:45], v[44:45], v[76:77]
	v_lshl_add_u64 v[64:65], v[64:65], 0, v[140:141]
	v_pk_add_f32 v[58:59], v[58:59], v[66:67]
	v_pk_add_f32 v[46:47], v[46:47], v[78:79]
	v_pk_add_f32 v[42:43], v[42:43], v[74:75]
	v_pk_add_f32 v[40:41], v[40:41], v[72:73]
	global_store_dwordx4 v[64:65], v[60:63], off nt
	global_store_dwordx4 v[64:65], v[56:59], off offset:16 nt
	global_store_dwordx4 v[64:65], v[44:47], off offset:128 nt
	global_store_dwordx4 v[64:65], v[40:43], off offset:144 nt
	v_pk_add_f32 v[32:33], v[32:33], v[88:89]
	v_pk_add_f32 v[44:45], v[48:49], v[80:81]
	v_lshl_add_u64 v[48:49], s[78:79], 0, v[98:99]
	v_pk_add_f32 v[42:43], v[54:55], v[86:87]
	v_pk_add_f32 v[40:41], v[52:53], v[84:85]
	v_lshl_add_u64 v[48:49], v[48:49], 0, v[140:141]
	v_pk_add_f32 v[46:47], v[50:51], v[82:83]
	v_pk_add_f32 v[38:39], v[38:39], v[94:95]
	v_pk_add_f32 v[36:37], v[36:37], v[92:93]
	v_pk_add_f32 v[34:35], v[34:35], v[90:91]
	global_store_dwordx4 v[48:49], v[40:43], off nt
	global_store_dwordx4 v[48:49], v[44:47], off offset:16 nt
	global_store_dwordx4 v[48:49], v[36:39], off offset:128 nt
	global_store_dwordx4 v[48:49], v[32:35], off offset:144 nt
	s_nop 1
	v_add_u32_e32 v32, 0xa0, v144
	v_ashrrev_i32_e32 v33, 31, v32
	v_lshlrev_b64 v[60:61], 12, v[32:33]
	v_lshl_add_u64 v[48:49], v[142:143], 0, v[60:61]
	global_load_dwordx4 v[40:43], v[48:49], off offset:16
	global_load_dwordx4 v[44:47], v[48:49], off
	global_load_dwordx4 v[32:35], v[48:49], off offset:144
	global_load_dwordx4 v[36:39], v[48:49], off offset:128
	v_add_u32_e32 v48, 0xb0, v144
	v_ashrrev_i32_e32 v49, 31, v48
	v_lshlrev_b64 v[62:63], 12, v[48:49]
	v_lshl_add_u64 v[68:69], v[142:143], 0, v[62:63]
	global_load_dwordx4 v[48:51], v[68:69], off offset:16
	global_load_dwordx4 v[56:59], v[68:69], off
	global_load_dwordx4 v[52:55], v[68:69], off offset:144
	global_load_dwordx4 v[64:67], v[68:69], off offset:128
	s_waitcnt vmcnt(0)
	v_pk_add_f32 v[26:27], v[26:27], v[42:43]
	v_pk_add_f32 v[30:31], v[30:31], v[46:47]
	v_pk_add_f32 v[12:13], v[12:13], v[32:33]
	v_lshl_add_u64 v[32:33], s[78:79], 0, v[60:61]
	v_pk_add_f32 v[28:29], v[28:29], v[44:45]
	v_lshl_add_u64 v[32:33], v[32:33], 0, v[140:141]
	v_pk_add_f32 v[24:25], v[24:25], v[40:41]
	v_pk_add_f32 v[22:23], v[22:23], v[38:39]
	v_pk_add_f32 v[20:21], v[20:21], v[36:37]
	v_pk_add_f32 v[14:15], v[14:15], v[34:35]
	global_store_dwordx4 v[32:33], v[28:31], off nt
	global_store_dwordx4 v[32:33], v[24:27], off offset:16 nt
	global_store_dwordx4 v[32:33], v[20:23], off offset:128 nt
	global_store_dwordx4 v[32:33], v[12:15], off offset:144 nt
	v_pk_add_f32 v[10:11], v[10:11], v[50:51]
	v_pk_add_f32 v[8:9], v[8:9], v[48:49]
	v_pk_add_f32 v[12:13], v[16:17], v[56:57]
	v_lshl_add_u64 v[16:17], s[78:79], 0, v[62:63]
	v_pk_add_f32 v[14:15], v[18:19], v[58:59]
	v_lshl_add_u64 v[16:17], v[16:17], 0, v[140:141]
	v_pk_add_f32 v[6:7], v[6:7], v[66:67]
	v_pk_add_f32 v[4:5], v[4:5], v[64:65]
	v_pk_add_f32 v[2:3], v[2:3], v[54:55]
	v_pk_add_f32 v[0:1], v[0:1], v[52:53]
	global_store_dwordx4 v[16:17], v[12:15], off nt
	global_store_dwordx4 v[16:17], v[8:11], off offset:16 nt
	global_store_dwordx4 v[16:17], v[4:7], off offset:128 nt
	global_store_dwordx4 v[16:17], v[0:3], off offset:144 nt
	s_cbranch_vccz .LBB0_877
	s_waitcnt vmcnt(0)
	s_cmpk_gt_u32 s16, 0xff
	s_cbranch_scc1 .LBB0_892
	s_barrier
